# K-loops: MFMAs inside each 8-MFMA group issued in snake order (weight-fragment operand repeats on consecutive MFMAs)
# baseline (speedup 1.0000x reference)
.LBB0_207:
	ds_read_b128 v[156:159], v152
	ds_read_b128 v[160:163], v152 offset:1024
	ds_read_b128 v[164:167], v152 offset:2048
	ds_read_b128 v[168:171], v152 offset:3072
	ds_read_b128 v[172:175], v153
	ds_read_b128 v[176:179], v153 offset:1024
	ds_read_b128 v[180:183], v153 offset:2048
	ds_read_b128 v[184:187], v153 offset:3072
	s_add_u32 s36, s0, 0xfffe0080
	s_addc_u32 s37, s1, -1
	s_cmp_eq_u32 s62, 4
	s_cselect_b32 s39, s25, s37
	s_cselect_b32 s38, s27, s36
	s_cselect_b32 s37, s29, s61
	s_cselect_b32 s36, s28, s60
	v_lshl_add_u64 v[146:147], s[0:1], 0, v[138:139]
	s_add_i32 m0, s35, 0xc000
	ds_read_b128 v[188:191], v154
	ds_read_b128 v[192:195], v154 offset:1024
	ds_read_b128 v[196:199], v154 offset:2048
	ds_read_b128 v[200:203], v154 offset:3072
	ds_read_b128 v[204:207], v154 offset:4096
	ds_read_b128 v[208:211], v154 offset:5120
	ds_read_b128 v[212:215], v154 offset:6144
	ds_read_b128 v[216:219], v154 offset:7168
	global_load_lds_dwordx4 v[146:147], off
	v_lshl_add_u64 v[146:147], s[0:1], 0, v[140:141]
	s_add_i32 m0, s35, 0xe000
	s_nop 0
	global_load_lds_dwordx4 v[146:147], off
	s_waitcnt vmcnt(8)
	s_waitcnt lgkmcnt(0)
	s_barrier
	s_setprio 1
	s_waitcnt lgkmcnt(0)
	v_mfma_f32_16x16x32_bf16 v[126:129], v[156:159], v[188:191], v[126:129]
	v_mfma_f32_16x16x32_bf16 v[122:125], v[164:167], v[188:191], v[122:125]
	v_mfma_f32_16x16x32_bf16 v[110:113], v[164:167], v[196:199], v[110:113]
	v_mfma_f32_16x16x32_bf16 v[118:121], v[156:159], v[196:199], v[118:121]
	v_mfma_f32_16x16x32_bf16 v[102:105], v[156:159], v[204:207], v[102:105]
	v_mfma_f32_16x16x32_bf16 v[94:97], v[164:167], v[204:207], v[94:97]
	v_mfma_f32_16x16x32_bf16 v[78:81], v[164:167], v[212:215], v[78:81]
	v_mfma_f32_16x16x32_bf16 v[86:89], v[156:159], v[212:215], v[86:89]
	v_mfma_f32_16x16x32_bf16 v[126:129], v[160:163], v[192:195], v[126:129]
	v_mfma_f32_16x16x32_bf16 v[122:125], v[168:171], v[192:195], v[122:125]
	v_mfma_f32_16x16x32_bf16 v[110:113], v[168:171], v[200:203], v[110:113]
	v_mfma_f32_16x16x32_bf16 v[118:121], v[160:163], v[200:203], v[118:121]
	v_mfma_f32_16x16x32_bf16 v[102:105], v[160:163], v[208:211], v[102:105]
	v_mfma_f32_16x16x32_bf16 v[94:97], v[168:171], v[208:211], v[94:97]
	v_mfma_f32_16x16x32_bf16 v[78:81], v[168:171], v[216:219], v[78:81]
	v_mfma_f32_16x16x32_bf16 v[86:89], v[160:163], v[216:219], v[86:89]
	s_setprio 0
	s_setprio 1
	v_mfma_f32_16x16x32_bf16 v[114:117], v[172:175], v[188:191], v[114:117]
	v_mfma_f32_16x16x32_bf16 v[106:109], v[180:183], v[188:191], v[106:109]
	v_mfma_f32_16x16x32_bf16 v[90:93], v[180:183], v[196:199], v[90:93]
	v_mfma_f32_16x16x32_bf16 v[98:101], v[172:175], v[196:199], v[98:101]
	v_mfma_f32_16x16x32_bf16 v[82:85], v[172:175], v[204:207], v[82:85]
	v_mfma_f32_16x16x32_bf16 v[74:77], v[180:183], v[204:207], v[74:77]
	v_mfma_f32_16x16x32_bf16 v[66:69], v[180:183], v[212:215], v[66:69]
	v_mfma_f32_16x16x32_bf16 v[70:73], v[172:175], v[212:215], v[70:73]
	v_mfma_f32_16x16x32_bf16 v[114:117], v[176:179], v[192:195], v[114:117]
	v_mfma_f32_16x16x32_bf16 v[106:109], v[184:187], v[192:195], v[106:109]
	v_mfma_f32_16x16x32_bf16 v[90:93], v[184:187], v[200:203], v[90:93]
	v_mfma_f32_16x16x32_bf16 v[98:101], v[176:179], v[200:203], v[98:101]
	v_mfma_f32_16x16x32_bf16 v[82:85], v[176:179], v[208:211], v[82:85]
	v_mfma_f32_16x16x32_bf16 v[74:77], v[184:187], v[208:211], v[74:77]
	v_mfma_f32_16x16x32_bf16 v[66:69], v[184:187], v[216:219], v[66:69]
	v_mfma_f32_16x16x32_bf16 v[70:73], v[176:179], v[216:219], v[70:73]
	s_setprio 0
	s_barrier
	s_add_i32 s63, s53, s43
	v_lshl_add_u64 v[146:147], s[36:37], 0, v[132:133]
	s_mov_b32 m0, s63
	ds_read_b128 v[188:191], v154 offset:16384
	ds_read_b128 v[192:195], v154 offset:17408
	ds_read_b128 v[196:199], v154 offset:18432
	ds_read_b128 v[200:203], v154 offset:19456
	ds_read_b128 v[204:207], v154 offset:20480
	ds_read_b128 v[208:211], v154 offset:21504
	ds_read_b128 v[212:215], v154 offset:22528
	ds_read_b128 v[216:219], v154 offset:23552
	global_load_lds_dwordx4 v[146:147], off
	s_add_i32 m0, s63, 0x2000
	s_add_u32 s64, s36, 0x80000
	v_lshl_add_u64 v[220:221], s[36:37], 0, v[136:137]
	s_addc_u32 s65, s37, 0
	s_add_i32 s63, s54, s43
	global_load_lds_dwordx4 v[220:221], off
	v_lshl_add_u64 v[222:223], s[64:65], 0, v[132:133]
	s_mov_b32 m0, s63
	v_lshl_add_u64 v[224:225], s[38:39], 0, v[134:135]
	global_load_lds_dwordx4 v[222:223], off
	v_lshl_add_u64 v[222:223], s[64:65], 0, v[136:137]
	s_add_i32 m0, s63, 0x2000
	s_nop 0
	global_load_lds_dwordx4 v[222:223], off
	v_lshl_add_u64 v[222:223], s[38:39], 0, v[130:131]
	s_mov_b32 m0, s35
	s_nop 0
	global_load_lds_dwordx4 v[222:223], off
	s_mov_b32 m0, s46
	s_nop 0
	global_load_lds_dwordx4 v[224:225], off
	s_waitcnt vmcnt(8)
	s_waitcnt lgkmcnt(0)
	s_barrier
	s_setprio 1
	s_waitcnt lgkmcnt(0)
	v_mfma_f32_16x16x32_bf16 v[62:65], v[156:159], v[188:191], v[62:65]
	v_mfma_f32_16x16x32_bf16 v[58:61], v[164:167], v[188:191], v[58:61]
	v_mfma_f32_16x16x32_bf16 v[46:49], v[164:167], v[196:199], v[46:49]
	v_mfma_f32_16x16x32_bf16 v[54:57], v[156:159], v[196:199], v[54:57]
	v_mfma_f32_16x16x32_bf16 v[38:41], v[156:159], v[204:207], v[38:41]
	v_mfma_f32_16x16x32_bf16 v[30:33], v[164:167], v[204:207], v[30:33]
	v_mfma_f32_16x16x32_bf16 v[14:17], v[164:167], v[212:215], v[14:17]
	v_mfma_f32_16x16x32_bf16 v[22:25], v[156:159], v[212:215], v[22:25]
	v_mfma_f32_16x16x32_bf16 v[62:65], v[160:163], v[192:195], v[62:65]
	v_mfma_f32_16x16x32_bf16 v[58:61], v[168:171], v[192:195], v[58:61]
	v_mfma_f32_16x16x32_bf16 v[46:49], v[168:171], v[200:203], v[46:49]
	v_mfma_f32_16x16x32_bf16 v[54:57], v[160:163], v[200:203], v[54:57]
	v_mfma_f32_16x16x32_bf16 v[38:41], v[160:163], v[208:211], v[38:41]
	v_mfma_f32_16x16x32_bf16 v[30:33], v[168:171], v[208:211], v[30:33]
	v_mfma_f32_16x16x32_bf16 v[14:17], v[168:171], v[216:219], v[14:17]
	v_mfma_f32_16x16x32_bf16 v[22:25], v[160:163], v[216:219], v[22:25]
	s_setprio 0
	s_setprio 1
	v_mfma_f32_16x16x32_bf16 v[50:53], v[172:175], v[188:191], v[50:53]
	v_mfma_f32_16x16x32_bf16 v[42:45], v[180:183], v[188:191], v[42:45]
	v_mfma_f32_16x16x32_bf16 v[26:29], v[180:183], v[196:199], v[26:29]
	v_mfma_f32_16x16x32_bf16 v[34:37], v[172:175], v[196:199], v[34:37]
	v_mfma_f32_16x16x32_bf16 v[18:21], v[172:175], v[204:207], v[18:21]
	v_mfma_f32_16x16x32_bf16 v[10:13], v[180:183], v[204:207], v[10:13]
	v_mfma_f32_16x16x32_bf16 v[2:5], v[180:183], v[212:215], v[2:5]
	v_mfma_f32_16x16x32_bf16 v[6:9], v[172:175], v[212:215], v[6:9]
	v_mfma_f32_16x16x32_bf16 v[50:53], v[176:179], v[192:195], v[50:53]
	v_mfma_f32_16x16x32_bf16 v[42:45], v[184:187], v[192:195], v[42:45]
	v_mfma_f32_16x16x32_bf16 v[26:29], v[184:187], v[200:203], v[26:29]
	v_mfma_f32_16x16x32_bf16 v[34:37], v[176:179], v[200:203], v[34:37]
	v_mfma_f32_16x16x32_bf16 v[18:21], v[176:179], v[208:211], v[18:21]
	v_mfma_f32_16x16x32_bf16 v[10:13], v[184:187], v[208:211], v[10:13]
	v_mfma_f32_16x16x32_bf16 v[2:5], v[184:187], v[216:219], v[2:5]
	v_mfma_f32_16x16x32_bf16 v[6:9], v[176:179], v[216:219], v[6:9]
	s_setprio 0
	s_barrier
	s_add_i32 s63, 0, 0x18000
	v_add_u32_e32 v155, s63, v150
	s_add_i32 s64, 0, 0x1c000
	ds_read_b128 v[156:159], v155
	ds_read_b128 v[160:163], v155 offset:1024
	ds_read_b128 v[164:167], v155 offset:2048
	ds_read_b128 v[168:171], v155 offset:3072
	v_add_u32_e32 v155, s64, v150
	ds_read_b128 v[172:175], v155
	ds_read_b128 v[176:179], v155 offset:1024
	ds_read_b128 v[180:183], v155 offset:2048
	ds_read_b128 v[184:187], v155 offset:3072
	s_add_u32 s38, s38, 0x20000
	s_addc_u32 s39, s39, 0
	s_mov_b32 m0, s47
	v_lshl_add_u64 v[226:227], s[38:39], 0, v[130:131]
	ds_read_b128 v[188:191], v154 offset:32768
	ds_read_b128 v[192:195], v154 offset:33792
	ds_read_b128 v[196:199], v154 offset:34816
	ds_read_b128 v[200:203], v154 offset:35840
	ds_read_b128 v[204:207], v154 offset:36864
	ds_read_b128 v[208:211], v154 offset:37888
	ds_read_b128 v[212:215], v154 offset:38912
	ds_read_b128 v[216:219], v154 offset:39936
	global_load_lds_dwordx4 v[226:227], off
	v_lshl_add_u64 v[226:227], s[38:39], 0, v[134:135]
	s_mov_b32 m0, s48
	s_nop 0
	global_load_lds_dwordx4 v[226:227], off
	s_waitcnt vmcnt(8)
	s_waitcnt lgkmcnt(0)
	s_barrier
	s_setprio 1
	s_waitcnt lgkmcnt(0)
	v_mfma_f32_16x16x32_bf16 v[126:129], v[156:159], v[188:191], v[126:129]
	v_mfma_f32_16x16x32_bf16 v[122:125], v[164:167], v[188:191], v[122:125]
	v_mfma_f32_16x16x32_bf16 v[110:113], v[164:167], v[196:199], v[110:113]
	v_mfma_f32_16x16x32_bf16 v[118:121], v[156:159], v[196:199], v[118:121]
	v_mfma_f32_16x16x32_bf16 v[102:105], v[156:159], v[204:207], v[102:105]
	v_mfma_f32_16x16x32_bf16 v[94:97], v[164:167], v[204:207], v[94:97]
	v_mfma_f32_16x16x32_bf16 v[78:81], v[164:167], v[212:215], v[78:81]
	v_mfma_f32_16x16x32_bf16 v[86:89], v[156:159], v[212:215], v[86:89]
	v_mfma_f32_16x16x32_bf16 v[126:129], v[160:163], v[192:195], v[126:129]
	v_mfma_f32_16x16x32_bf16 v[122:125], v[168:171], v[192:195], v[122:125]
	v_mfma_f32_16x16x32_bf16 v[110:113], v[168:171], v[200:203], v[110:113]
	v_mfma_f32_16x16x32_bf16 v[118:121], v[160:163], v[200:203], v[118:121]
	v_mfma_f32_16x16x32_bf16 v[102:105], v[160:163], v[208:211], v[102:105]
	v_mfma_f32_16x16x32_bf16 v[94:97], v[168:171], v[208:211], v[94:97]
	v_mfma_f32_16x16x32_bf16 v[78:81], v[168:171], v[216:219], v[78:81]
	v_mfma_f32_16x16x32_bf16 v[86:89], v[160:163], v[216:219], v[86:89]
	s_setprio 0
	s_setprio 1
	v_mfma_f32_16x16x32_bf16 v[114:117], v[172:175], v[188:191], v[114:117]
	v_mfma_f32_16x16x32_bf16 v[106:109], v[180:183], v[188:191], v[106:109]
	v_mfma_f32_16x16x32_bf16 v[90:93], v[180:183], v[196:199], v[90:93]
	v_mfma_f32_16x16x32_bf16 v[98:101], v[172:175], v[196:199], v[98:101]
	v_mfma_f32_16x16x32_bf16 v[82:85], v[172:175], v[204:207], v[82:85]
	v_mfma_f32_16x16x32_bf16 v[74:77], v[180:183], v[204:207], v[74:77]
	v_mfma_f32_16x16x32_bf16 v[66:69], v[180:183], v[212:215], v[66:69]
	v_mfma_f32_16x16x32_bf16 v[70:73], v[172:175], v[212:215], v[70:73]
	v_mfma_f32_16x16x32_bf16 v[114:117], v[176:179], v[192:195], v[114:117]
	v_mfma_f32_16x16x32_bf16 v[106:109], v[184:187], v[192:195], v[106:109]
	v_mfma_f32_16x16x32_bf16 v[90:93], v[184:187], v[200:203], v[90:93]
	v_mfma_f32_16x16x32_bf16 v[98:101], v[176:179], v[200:203], v[98:101]
	v_mfma_f32_16x16x32_bf16 v[82:85], v[176:179], v[208:211], v[82:85]
	v_mfma_f32_16x16x32_bf16 v[74:77], v[184:187], v[208:211], v[74:77]
	v_mfma_f32_16x16x32_bf16 v[66:69], v[184:187], v[216:219], v[66:69]
	v_mfma_f32_16x16x32_bf16 v[70:73], v[176:179], v[216:219], v[70:73]
	s_setprio 0
	s_barrier
	s_add_i32 s38, s63, s43
	v_lshl_add_u64 v[146:147], v[146:147], 0, s[8:9]
	s_mov_b32 m0, s38
	ds_read_b128 v[188:191], v154 offset:49152
	ds_read_b128 v[192:195], v154 offset:50176
	ds_read_b128 v[196:199], v154 offset:51200
	ds_read_b128 v[200:203], v154 offset:52224
	ds_read_b128 v[204:207], v154 offset:53248
	ds_read_b128 v[208:211], v154 offset:54272
	ds_read_b128 v[212:215], v154 offset:55296
	ds_read_b128 v[216:219], v154 offset:56320
	global_load_lds_dwordx4 v[146:147], off
	s_add_i32 m0, s38, 0x2000
	s_add_u32 s36, s36, 0x80080
	v_lshl_add_u64 v[146:147], v[220:221], 0, s[8:9]
	s_addc_u32 s37, s37, 0
	s_add_i32 s38, s64, s43
	global_load_lds_dwordx4 v[146:147], off
	v_lshl_add_u64 v[146:147], s[36:37], 0, v[132:133]
	s_mov_b32 m0, s38
	s_nop 0
	global_load_lds_dwordx4 v[146:147], off
	v_lshl_add_u64 v[146:147], s[36:37], 0, v[136:137]
	s_add_i32 m0, s38, 0x2000
	s_nop 0
	global_load_lds_dwordx4 v[146:147], off
	v_lshl_add_u64 v[146:147], v[222:223], 0, s[8:9]
	s_mov_b32 m0, s50
	s_nop 0
	global_load_lds_dwordx4 v[146:147], off
	v_lshl_add_u64 v[146:147], v[224:225], 0, s[8:9]
	s_mov_b32 m0, s51
	s_nop 0
	global_load_lds_dwordx4 v[146:147], off
	s_waitcnt vmcnt(8)
	s_waitcnt lgkmcnt(0)
	s_barrier
	s_setprio 1
	s_waitcnt lgkmcnt(0)
	v_mfma_f32_16x16x32_bf16 v[62:65], v[156:159], v[188:191], v[62:65]
	v_mfma_f32_16x16x32_bf16 v[58:61], v[164:167], v[188:191], v[58:61]
	v_mfma_f32_16x16x32_bf16 v[46:49], v[164:167], v[196:199], v[46:49]
	v_mfma_f32_16x16x32_bf16 v[54:57], v[156:159], v[196:199], v[54:57]
	v_mfma_f32_16x16x32_bf16 v[38:41], v[156:159], v[204:207], v[38:41]
	v_mfma_f32_16x16x32_bf16 v[30:33], v[164:167], v[204:207], v[30:33]
	v_mfma_f32_16x16x32_bf16 v[14:17], v[164:167], v[212:215], v[14:17]
	v_mfma_f32_16x16x32_bf16 v[22:25], v[156:159], v[212:215], v[22:25]
	v_mfma_f32_16x16x32_bf16 v[62:65], v[160:163], v[192:195], v[62:65]
	v_mfma_f32_16x16x32_bf16 v[58:61], v[168:171], v[192:195], v[58:61]
	v_mfma_f32_16x16x32_bf16 v[46:49], v[168:171], v[200:203], v[46:49]
	v_mfma_f32_16x16x32_bf16 v[54:57], v[160:163], v[200:203], v[54:57]
	v_mfma_f32_16x16x32_bf16 v[38:41], v[160:163], v[208:211], v[38:41]
	v_mfma_f32_16x16x32_bf16 v[30:33], v[168:171], v[208:211], v[30:33]
	v_mfma_f32_16x16x32_bf16 v[14:17], v[168:171], v[216:219], v[14:17]
	v_mfma_f32_16x16x32_bf16 v[22:25], v[160:163], v[216:219], v[22:25]
	s_setprio 0
	s_setprio 1
	v_mfma_f32_16x16x32_bf16 v[50:53], v[172:175], v[188:191], v[50:53]
	v_mfma_f32_16x16x32_bf16 v[42:45], v[180:183], v[188:191], v[42:45]
	v_mfma_f32_16x16x32_bf16 v[26:29], v[180:183], v[196:199], v[26:29]
	v_mfma_f32_16x16x32_bf16 v[34:37], v[172:175], v[196:199], v[34:37]
	v_mfma_f32_16x16x32_bf16 v[18:21], v[172:175], v[204:207], v[18:21]
	v_mfma_f32_16x16x32_bf16 v[10:13], v[180:183], v[204:207], v[10:13]
	v_mfma_f32_16x16x32_bf16 v[2:5], v[180:183], v[212:215], v[2:5]
	v_mfma_f32_16x16x32_bf16 v[6:9], v[172:175], v[212:215], v[6:9]
	v_mfma_f32_16x16x32_bf16 v[50:53], v[176:179], v[192:195], v[50:53]
	v_mfma_f32_16x16x32_bf16 v[42:45], v[184:187], v[192:195], v[42:45]
	v_mfma_f32_16x16x32_bf16 v[26:29], v[184:187], v[200:203], v[26:29]
	v_mfma_f32_16x16x32_bf16 v[34:37], v[176:179], v[200:203], v[34:37]
	v_mfma_f32_16x16x32_bf16 v[18:21], v[176:179], v[208:211], v[18:21]
	v_mfma_f32_16x16x32_bf16 v[10:13], v[184:187], v[208:211], v[10:13]
	v_mfma_f32_16x16x32_bf16 v[2:5], v[184:187], v[216:219], v[2:5]
	v_mfma_f32_16x16x32_bf16 v[6:9], v[176:179], v[216:219], v[6:9]
	s_setprio 0
	s_barrier
	s_add_i32 s62, s62, 2
	s_add_u32 s0, s0, 0x100
	s_addc_u32 s1, s1, 0
	s_add_u32 s60, s60, 0x100
	s_addc_u32 s61, s61, 0
	s_cmp_gt_u32 s62, 5
	s_cbranch_scc0 .LBB0_207
	s_and_b64 vcc, exec, s[10:11]
	s_cbranch_vccz .LBB0_210
	s_barrier

.LBB0_290:
	s_add_u32 s12, s60, s10
	s_addc_u32 s13, s61, s11
	s_add_u32 s12, s12, 0x100
	s_addc_u32 s13, s13, 0
	s_add_u32 s97, s28, s10
	s_addc_u32 vcc_lo, s29, s11
	s_add_i32 vcc_hi, 0, 0x10000
	s_cmpk_eq_i32 s10, 0xf00
	s_cselect_b32 s41, s63, s13
	s_cselect_b32 s40, s94, s12
	v_add_u32_e32 v154, vcc_hi, v169
	s_cselect_b32 s13, s67, vcc_lo
	s_cselect_b32 s12, s95, s97
	s_add_i32 s97, 0, 0x14000
	ds_read_b128 v[146:149], v154
	ds_read_b128 v[150:153], v154 offset:1024
	ds_read_b128 v[164:167], v154 offset:2048
	ds_read_b128 v[172:175], v154 offset:3072
	v_add_u32_e32 v154, s97, v169
	ds_read_b128 v[176:179], v154
	ds_read_b128 v[180:183], v154 offset:1024
	ds_read_b128 v[184:187], v154 offset:2048
	ds_read_b128 v[188:191], v154 offset:3072
	v_lshl_add_u64 v[196:197], v[142:143], 0, s[10:11]
	s_add_i32 m0, s81, 0xc000
	ds_read_b128 v[200:203], v171
	ds_read_b128 v[204:207], v171 offset:1024
	ds_read_b128 v[208:211], v171 offset:2048
	ds_read_b128 v[212:215], v171 offset:3072
	ds_read_b128 v[216:219], v171 offset:4096
	ds_read_b128 v[220:223], v171 offset:5120
	ds_read_b128 v[224:227], v171 offset:6144
	ds_read_b128 v[228:231], v171 offset:7168
	global_load_lds_dwordx4 v[196:197], off
	v_lshl_add_u64 v[196:197], v[144:145], 0, s[10:11]
	s_add_i32 m0, s81, 0xe000
	s_nop 0
	global_load_lds_dwordx4 v[196:197], off
	s_waitcnt vmcnt(8)
	s_waitcnt lgkmcnt(0)
	s_barrier
	s_setprio 1
	s_waitcnt lgkmcnt(0)
	v_mfma_f32_16x16x32_bf16 v[126:129], v[146:149], v[200:203], v[126:129]
	v_mfma_f32_16x16x32_bf16 v[122:125], v[164:167], v[200:203], v[122:125]
	v_mfma_f32_16x16x32_bf16 v[114:117], v[164:167], v[208:211], v[114:117]
	v_mfma_f32_16x16x32_bf16 v[118:121], v[146:149], v[208:211], v[118:121]
	v_mfma_f32_16x16x32_bf16 v[110:113], v[146:149], v[216:219], v[110:113]
	v_mfma_f32_16x16x32_bf16 v[106:109], v[164:167], v[216:219], v[106:109]
	v_mfma_f32_16x16x32_bf16 v[98:101], v[164:167], v[224:227], v[98:101]
	v_mfma_f32_16x16x32_bf16 v[102:105], v[146:149], v[224:227], v[102:105]
	v_mfma_f32_16x16x32_bf16 v[126:129], v[150:153], v[204:207], v[126:129]
	v_mfma_f32_16x16x32_bf16 v[122:125], v[172:175], v[204:207], v[122:125]
	v_mfma_f32_16x16x32_bf16 v[114:117], v[172:175], v[212:215], v[114:117]
	v_mfma_f32_16x16x32_bf16 v[118:121], v[150:153], v[212:215], v[118:121]
	v_mfma_f32_16x16x32_bf16 v[110:113], v[150:153], v[220:223], v[110:113]
	v_mfma_f32_16x16x32_bf16 v[106:109], v[172:175], v[220:223], v[106:109]
	v_mfma_f32_16x16x32_bf16 v[98:101], v[172:175], v[228:231], v[98:101]
	v_mfma_f32_16x16x32_bf16 v[102:105], v[150:153], v[228:231], v[102:105]
	s_setprio 0
	s_setprio 1
	v_mfma_f32_16x16x32_bf16 v[94:97], v[176:179], v[200:203], v[94:97]
	v_mfma_f32_16x16x32_bf16 v[90:93], v[184:187], v[200:203], v[90:93]
	v_mfma_f32_16x16x32_bf16 v[82:85], v[184:187], v[208:211], v[82:85]
	v_mfma_f32_16x16x32_bf16 v[86:89], v[176:179], v[208:211], v[86:89]
	v_mfma_f32_16x16x32_bf16 v[78:81], v[176:179], v[216:219], v[78:81]
	v_mfma_f32_16x16x32_bf16 v[74:77], v[184:187], v[216:219], v[74:77]
	v_mfma_f32_16x16x32_bf16 v[66:69], v[184:187], v[224:227], v[66:69]
	v_mfma_f32_16x16x32_bf16 v[70:73], v[176:179], v[224:227], v[70:73]
	v_mfma_f32_16x16x32_bf16 v[94:97], v[180:183], v[204:207], v[94:97]
	v_mfma_f32_16x16x32_bf16 v[90:93], v[188:191], v[204:207], v[90:93]
	v_mfma_f32_16x16x32_bf16 v[82:85], v[188:191], v[212:215], v[82:85]
	v_mfma_f32_16x16x32_bf16 v[86:89], v[180:183], v[212:215], v[86:89]
	v_mfma_f32_16x16x32_bf16 v[78:81], v[180:183], v[220:223], v[78:81]
	v_mfma_f32_16x16x32_bf16 v[74:77], v[188:191], v[220:223], v[74:77]
	v_mfma_f32_16x16x32_bf16 v[66:69], v[188:191], v[228:231], v[66:69]
	v_mfma_f32_16x16x32_bf16 v[70:73], v[180:183], v[228:231], v[70:73]
	s_setprio 0
	s_barrier
	s_add_i32 vcc_lo, vcc_hi, s80
	v_lshl_add_u64 v[196:197], s[12:13], 0, v[132:133]
	s_mov_b32 m0, vcc_lo
	ds_read_b128 v[200:203], v171 offset:16384
	ds_read_b128 v[204:207], v171 offset:17408
	ds_read_b128 v[208:211], v171 offset:18432
	ds_read_b128 v[212:215], v171 offset:19456
	ds_read_b128 v[216:219], v171 offset:20480
	ds_read_b128 v[220:223], v171 offset:21504
	ds_read_b128 v[224:227], v171 offset:22528
	ds_read_b128 v[228:231], v171 offset:23552
	global_load_lds_dwordx4 v[196:197], off
	s_add_i32 m0, vcc_lo, 0x2000
	s_add_u32 vcc_lo, s12, 0x80000
	v_lshl_add_u64 v[232:233], s[12:13], 0, v[136:137]
	s_addc_u32 vcc_hi, s13, 0
	s_add_i32 s97, s97, s80
	global_load_lds_dwordx4 v[232:233], off
	v_lshl_add_u64 v[234:235], vcc, 0, v[132:133]
	s_mov_b32 m0, s97
	v_lshl_add_u64 v[236:237], s[40:41], 0, v[134:135]
	global_load_lds_dwordx4 v[234:235], off
	v_lshl_add_u64 v[234:235], vcc, 0, v[136:137]
	s_add_i32 m0, s97, 0x2000
	s_nop 0
	global_load_lds_dwordx4 v[234:235], off
	v_lshl_add_u64 v[234:235], s[40:41], 0, v[130:131]
	s_mov_b32 m0, s81
	s_nop 0
	global_load_lds_dwordx4 v[234:235], off
	s_mov_b32 m0, s82
	s_nop 0
	global_load_lds_dwordx4 v[236:237], off
	s_waitcnt vmcnt(8)
	s_waitcnt lgkmcnt(0)
	s_barrier
	s_setprio 1
	s_waitcnt lgkmcnt(0)
	v_mfma_f32_16x16x32_bf16 v[62:65], v[146:149], v[200:203], v[62:65]
	v_mfma_f32_16x16x32_bf16 v[58:61], v[164:167], v[200:203], v[58:61]
	v_mfma_f32_16x16x32_bf16 v[50:53], v[164:167], v[208:211], v[50:53]
	v_mfma_f32_16x16x32_bf16 v[54:57], v[146:149], v[208:211], v[54:57]
	v_mfma_f32_16x16x32_bf16 v[46:49], v[146:149], v[216:219], v[46:49]
	v_mfma_f32_16x16x32_bf16 v[42:45], v[164:167], v[216:219], v[42:45]
	v_mfma_f32_16x16x32_bf16 v[34:37], v[164:167], v[224:227], v[34:37]
	v_mfma_f32_16x16x32_bf16 v[38:41], v[146:149], v[224:227], v[38:41]
	v_mfma_f32_16x16x32_bf16 v[62:65], v[150:153], v[204:207], v[62:65]
	v_mfma_f32_16x16x32_bf16 v[58:61], v[172:175], v[204:207], v[58:61]
	v_mfma_f32_16x16x32_bf16 v[50:53], v[172:175], v[212:215], v[50:53]
	v_mfma_f32_16x16x32_bf16 v[54:57], v[150:153], v[212:215], v[54:57]
	v_mfma_f32_16x16x32_bf16 v[46:49], v[150:153], v[220:223], v[46:49]
	v_mfma_f32_16x16x32_bf16 v[42:45], v[172:175], v[220:223], v[42:45]
	v_mfma_f32_16x16x32_bf16 v[34:37], v[172:175], v[228:231], v[34:37]
	v_mfma_f32_16x16x32_bf16 v[38:41], v[150:153], v[228:231], v[38:41]
	s_setprio 0
	s_setprio 1
	v_mfma_f32_16x16x32_bf16 v[30:33], v[176:179], v[200:203], v[30:33]
	v_mfma_f32_16x16x32_bf16 v[26:29], v[184:187], v[200:203], v[26:29]
	v_mfma_f32_16x16x32_bf16 v[18:21], v[184:187], v[208:211], v[18:21]
	v_mfma_f32_16x16x32_bf16 v[22:25], v[176:179], v[208:211], v[22:25]
	v_mfma_f32_16x16x32_bf16 v[14:17], v[176:179], v[216:219], v[14:17]
	v_mfma_f32_16x16x32_bf16 v[10:13], v[184:187], v[216:219], v[10:13]
	v_mfma_f32_16x16x32_bf16 v[2:5], v[184:187], v[224:227], v[2:5]
	v_mfma_f32_16x16x32_bf16 v[6:9], v[176:179], v[224:227], v[6:9]
	v_mfma_f32_16x16x32_bf16 v[30:33], v[180:183], v[204:207], v[30:33]
	v_mfma_f32_16x16x32_bf16 v[26:29], v[188:191], v[204:207], v[26:29]
	v_mfma_f32_16x16x32_bf16 v[18:21], v[188:191], v[212:215], v[18:21]
	v_mfma_f32_16x16x32_bf16 v[22:25], v[180:183], v[212:215], v[22:25]
	v_mfma_f32_16x16x32_bf16 v[14:17], v[180:183], v[220:223], v[14:17]
	v_mfma_f32_16x16x32_bf16 v[10:13], v[188:191], v[220:223], v[10:13]
	v_mfma_f32_16x16x32_bf16 v[2:5], v[188:191], v[228:231], v[2:5]
	v_mfma_f32_16x16x32_bf16 v[6:9], v[180:183], v[228:231], v[6:9]
	s_setprio 0
	s_barrier
	s_add_i32 s97, 0, 0x18000
	v_add_u32_e32 v154, s97, v169
	s_add_i32 vcc_lo, 0, 0x1c000
	ds_read_b128 v[146:149], v154
	ds_read_b128 v[150:153], v154 offset:1024
	ds_read_b128 v[164:167], v154 offset:2048
	ds_read_b128 v[172:175], v154 offset:3072
	v_add_u32_e32 v154, vcc_lo, v169
	ds_read_b128 v[176:179], v154
	ds_read_b128 v[180:183], v154 offset:1024
	ds_read_b128 v[184:187], v154 offset:2048
	ds_read_b128 v[188:191], v154 offset:3072
	s_add_u32 s40, s40, 0x80000
	s_addc_u32 s41, s41, 0
	s_mov_b32 m0, s83
	v_lshl_add_u64 v[238:239], s[40:41], 0, v[130:131]
	ds_read_b128 v[200:203], v171 offset:32768
	ds_read_b128 v[204:207], v171 offset:33792
	ds_read_b128 v[208:211], v171 offset:34816
	ds_read_b128 v[212:215], v171 offset:35840
	ds_read_b128 v[216:219], v171 offset:36864
	ds_read_b128 v[220:223], v171 offset:37888
	ds_read_b128 v[224:227], v171 offset:38912
	ds_read_b128 v[228:231], v171 offset:39936
	global_load_lds_dwordx4 v[238:239], off
	v_lshl_add_u64 v[238:239], s[40:41], 0, v[134:135]
	s_mov_b32 m0, s84
	s_nop 0
	global_load_lds_dwordx4 v[238:239], off
	s_waitcnt vmcnt(8)
	s_waitcnt lgkmcnt(0)
	s_barrier
	s_setprio 1
	s_waitcnt lgkmcnt(0)
	v_mfma_f32_16x16x32_bf16 v[126:129], v[146:149], v[200:203], v[126:129]
	v_mfma_f32_16x16x32_bf16 v[122:125], v[164:167], v[200:203], v[122:125]
	v_mfma_f32_16x16x32_bf16 v[114:117], v[164:167], v[208:211], v[114:117]
	v_mfma_f32_16x16x32_bf16 v[118:121], v[146:149], v[208:211], v[118:121]
	v_mfma_f32_16x16x32_bf16 v[110:113], v[146:149], v[216:219], v[110:113]
	v_mfma_f32_16x16x32_bf16 v[106:109], v[164:167], v[216:219], v[106:109]
	v_mfma_f32_16x16x32_bf16 v[98:101], v[164:167], v[224:227], v[98:101]
	v_mfma_f32_16x16x32_bf16 v[102:105], v[146:149], v[224:227], v[102:105]
	v_mfma_f32_16x16x32_bf16 v[126:129], v[150:153], v[204:207], v[126:129]
	v_mfma_f32_16x16x32_bf16 v[122:125], v[172:175], v[204:207], v[122:125]
	v_mfma_f32_16x16x32_bf16 v[114:117], v[172:175], v[212:215], v[114:117]
	v_mfma_f32_16x16x32_bf16 v[118:121], v[150:153], v[212:215], v[118:121]
	v_mfma_f32_16x16x32_bf16 v[110:113], v[150:153], v[220:223], v[110:113]
	v_mfma_f32_16x16x32_bf16 v[106:109], v[172:175], v[220:223], v[106:109]
	v_mfma_f32_16x16x32_bf16 v[98:101], v[172:175], v[228:231], v[98:101]
	v_mfma_f32_16x16x32_bf16 v[102:105], v[150:153], v[228:231], v[102:105]
	s_setprio 0
	s_setprio 1
	v_mfma_f32_16x16x32_bf16 v[94:97], v[176:179], v[200:203], v[94:97]
	v_mfma_f32_16x16x32_bf16 v[90:93], v[184:187], v[200:203], v[90:93]
	v_mfma_f32_16x16x32_bf16 v[82:85], v[184:187], v[208:211], v[82:85]
	v_mfma_f32_16x16x32_bf16 v[86:89], v[176:179], v[208:211], v[86:89]
	v_mfma_f32_16x16x32_bf16 v[78:81], v[176:179], v[216:219], v[78:81]
	v_mfma_f32_16x16x32_bf16 v[74:77], v[184:187], v[216:219], v[74:77]
	v_mfma_f32_16x16x32_bf16 v[66:69], v[184:187], v[224:227], v[66:69]
	v_mfma_f32_16x16x32_bf16 v[70:73], v[176:179], v[224:227], v[70:73]
	v_mfma_f32_16x16x32_bf16 v[94:97], v[180:183], v[204:207], v[94:97]
	v_mfma_f32_16x16x32_bf16 v[90:93], v[188:191], v[204:207], v[90:93]
	v_mfma_f32_16x16x32_bf16 v[82:85], v[188:191], v[212:215], v[82:85]
	v_mfma_f32_16x16x32_bf16 v[86:89], v[180:183], v[212:215], v[86:89]
	v_mfma_f32_16x16x32_bf16 v[78:81], v[180:183], v[220:223], v[78:81]
	v_mfma_f32_16x16x32_bf16 v[74:77], v[188:191], v[220:223], v[74:77]
	v_mfma_f32_16x16x32_bf16 v[66:69], v[188:191], v[228:231], v[66:69]
	v_mfma_f32_16x16x32_bf16 v[70:73], v[180:183], v[228:231], v[70:73]
	s_setprio 0
	s_barrier
	s_add_i32 s40, s97, s80
	v_lshl_add_u64 v[196:197], v[196:197], 0, s[34:35]
	s_mov_b32 m0, s40
	ds_read_b128 v[200:203], v171 offset:49152
	ds_read_b128 v[204:207], v171 offset:50176
	ds_read_b128 v[208:211], v171 offset:51200
	ds_read_b128 v[212:215], v171 offset:52224
	ds_read_b128 v[216:219], v171 offset:53248
	ds_read_b128 v[220:223], v171 offset:54272
	ds_read_b128 v[224:227], v171 offset:55296
	ds_read_b128 v[228:231], v171 offset:56320
	global_load_lds_dwordx4 v[196:197], off
	s_add_i32 m0, s40, 0x2000
	s_add_u32 s12, s12, 0x80080
	v_lshl_add_u64 v[196:197], v[232:233], 0, s[34:35]
	s_addc_u32 s13, s13, 0
	s_add_i32 s40, vcc_lo, s80
	global_load_lds_dwordx4 v[196:197], off
	v_lshl_add_u64 v[196:197], s[12:13], 0, v[132:133]
	s_mov_b32 m0, s40
	s_nop 0
	global_load_lds_dwordx4 v[196:197], off
	v_lshl_add_u64 v[196:197], s[12:13], 0, v[136:137]
	s_add_i32 m0, s40, 0x2000
	s_nop 0
	global_load_lds_dwordx4 v[196:197], off
	v_lshl_add_u64 v[196:197], v[234:235], 0, s[34:35]
	s_mov_b32 m0, s85
	s_nop 0
	global_load_lds_dwordx4 v[196:197], off
	v_lshl_add_u64 v[196:197], v[236:237], 0, s[34:35]
	s_mov_b32 m0, s86
	s_nop 0
	global_load_lds_dwordx4 v[196:197], off
	s_waitcnt vmcnt(8)
	s_waitcnt lgkmcnt(0)
	s_barrier
	s_setprio 1
	s_waitcnt lgkmcnt(0)
	v_mfma_f32_16x16x32_bf16 v[62:65], v[146:149], v[200:203], v[62:65]
	v_mfma_f32_16x16x32_bf16 v[58:61], v[164:167], v[200:203], v[58:61]
	v_mfma_f32_16x16x32_bf16 v[50:53], v[164:167], v[208:211], v[50:53]
	v_mfma_f32_16x16x32_bf16 v[54:57], v[146:149], v[208:211], v[54:57]
	v_mfma_f32_16x16x32_bf16 v[46:49], v[146:149], v[216:219], v[46:49]
	v_mfma_f32_16x16x32_bf16 v[42:45], v[164:167], v[216:219], v[42:45]
	v_mfma_f32_16x16x32_bf16 v[34:37], v[164:167], v[224:227], v[34:37]
	v_mfma_f32_16x16x32_bf16 v[38:41], v[146:149], v[224:227], v[38:41]
	v_mfma_f32_16x16x32_bf16 v[62:65], v[150:153], v[204:207], v[62:65]
	v_mfma_f32_16x16x32_bf16 v[58:61], v[172:175], v[204:207], v[58:61]
	v_mfma_f32_16x16x32_bf16 v[50:53], v[172:175], v[212:215], v[50:53]
	v_mfma_f32_16x16x32_bf16 v[54:57], v[150:153], v[212:215], v[54:57]
	v_mfma_f32_16x16x32_bf16 v[46:49], v[150:153], v[220:223], v[46:49]
	v_mfma_f32_16x16x32_bf16 v[42:45], v[172:175], v[220:223], v[42:45]
	v_mfma_f32_16x16x32_bf16 v[34:37], v[172:175], v[228:231], v[34:37]
	v_mfma_f32_16x16x32_bf16 v[38:41], v[150:153], v[228:231], v[38:41]
	s_setprio 0
	s_setprio 1
	v_mfma_f32_16x16x32_bf16 v[30:33], v[176:179], v[200:203], v[30:33]
	v_mfma_f32_16x16x32_bf16 v[26:29], v[184:187], v[200:203], v[26:29]
	v_mfma_f32_16x16x32_bf16 v[18:21], v[184:187], v[208:211], v[18:21]
	v_mfma_f32_16x16x32_bf16 v[22:25], v[176:179], v[208:211], v[22:25]
	v_mfma_f32_16x16x32_bf16 v[14:17], v[176:179], v[216:219], v[14:17]
	v_mfma_f32_16x16x32_bf16 v[10:13], v[184:187], v[216:219], v[10:13]
	v_mfma_f32_16x16x32_bf16 v[2:5], v[184:187], v[224:227], v[2:5]
	v_mfma_f32_16x16x32_bf16 v[6:9], v[176:179], v[224:227], v[6:9]
	v_mfma_f32_16x16x32_bf16 v[30:33], v[180:183], v[204:207], v[30:33]
	v_mfma_f32_16x16x32_bf16 v[26:29], v[188:191], v[204:207], v[26:29]
	v_mfma_f32_16x16x32_bf16 v[18:21], v[188:191], v[212:215], v[18:21]
	v_mfma_f32_16x16x32_bf16 v[22:25], v[180:183], v[212:215], v[22:25]
	v_mfma_f32_16x16x32_bf16 v[14:17], v[180:183], v[220:223], v[14:17]
	v_mfma_f32_16x16x32_bf16 v[10:13], v[188:191], v[220:223], v[10:13]
	v_mfma_f32_16x16x32_bf16 v[2:5], v[188:191], v[228:231], v[2:5]
	v_mfma_f32_16x16x32_bf16 v[6:9], v[180:183], v[228:231], v[6:9]
	s_setprio 0
	s_barrier
	s_add_i32 s96, s96, 2
	s_add_u32 s10, s10, 0x100
	s_addc_u32 s11, s11, 0
	s_cmp_gt_u32 s96, 29
	s_cbranch_scc0 .LBB0_290
	s_and_b64 vcc, exec, s[56:57]
	s_cbranch_vccz .LBB0_293
	s_barrier

.LBB0_473:
	s_add_u32 s64, s56, s10
	s_addc_u32 s65, s57, s11
	s_add_u32 s64, s64, 0x100
	s_addc_u32 s65, s65, 0
	s_add_u32 vcc_lo, s93, s10
	s_addc_u32 vcc_hi, s94, s11
	s_add_i32 s16, 0, 0x10000
	s_cmpk_eq_i32 s10, 0xf00
	s_cselect_b32 s67, s55, s65
	s_cselect_b32 s66, s95, s64
	s_cselect_b32 s65, s53, vcc_hi
	s_cselect_b32 s64, s96, vcc_lo
	s_add_i32 s24, 0, 0x14000
	v_add_u32_e32 v146, s16, v197
	v_add_u32_e32 v182, s24, v197
	ds_read_b128 v[134:137], v146
	ds_read_b128 v[138:141], v146 offset:1024
	ds_read_b128 v[142:145], v146 offset:2048
	ds_read_b128 v[146:149], v146 offset:3072
	ds_read_b128 v[150:153], v182
	ds_read_b128 v[174:177], v182 offset:1024
	ds_read_b128 v[178:181], v182 offset:2048
	ds_read_b128 v[182:185], v182 offset:3072
	v_lshl_add_u64 v[190:191], v[130:131], 0, s[10:11]
	s_add_i32 m0, s80, 0xc000
	ds_read_b128 v[186:189], v200
	ds_read_b128 v[202:205], v200 offset:1024
	ds_read_b128 v[206:209], v200 offset:2048
	ds_read_b128 v[210:213], v200 offset:3072
	ds_read_b128 v[214:217], v200 offset:4096
	ds_read_b128 v[218:221], v200 offset:5120
	ds_read_b128 v[222:225], v200 offset:6144
	ds_read_b128 v[226:229], v200 offset:7168
	global_load_lds_dwordx4 v[190:191], off
	v_lshl_add_u64 v[190:191], v[132:133], 0, s[10:11]
	s_add_i32 m0, s80, 0xe000
	s_nop 0
	global_load_lds_dwordx4 v[190:191], off
	s_waitcnt vmcnt(8)
	s_waitcnt lgkmcnt(0)
	s_barrier
	s_setprio 1
	s_waitcnt lgkmcnt(0)
	v_mfma_f32_16x16x32_bf16 v[126:129], v[134:137], v[186:189], v[126:129]
	v_mfma_f32_16x16x32_bf16 v[122:125], v[142:145], v[186:189], v[122:125]
	v_mfma_f32_16x16x32_bf16 v[114:117], v[142:145], v[206:209], v[114:117]
	v_mfma_f32_16x16x32_bf16 v[118:121], v[134:137], v[206:209], v[118:121]
	v_mfma_f32_16x16x32_bf16 v[110:113], v[134:137], v[214:217], v[110:113]
	v_mfma_f32_16x16x32_bf16 v[106:109], v[142:145], v[214:217], v[106:109]
	v_mfma_f32_16x16x32_bf16 v[98:101], v[142:145], v[222:225], v[98:101]
	v_mfma_f32_16x16x32_bf16 v[102:105], v[134:137], v[222:225], v[102:105]
	v_mfma_f32_16x16x32_bf16 v[126:129], v[138:141], v[202:205], v[126:129]
	v_mfma_f32_16x16x32_bf16 v[122:125], v[146:149], v[202:205], v[122:125]
	v_mfma_f32_16x16x32_bf16 v[114:117], v[146:149], v[210:213], v[114:117]
	v_mfma_f32_16x16x32_bf16 v[118:121], v[138:141], v[210:213], v[118:121]
	v_mfma_f32_16x16x32_bf16 v[110:113], v[138:141], v[218:221], v[110:113]
	v_mfma_f32_16x16x32_bf16 v[106:109], v[146:149], v[218:221], v[106:109]
	v_mfma_f32_16x16x32_bf16 v[98:101], v[146:149], v[226:229], v[98:101]
	v_mfma_f32_16x16x32_bf16 v[102:105], v[138:141], v[226:229], v[102:105]
	s_setprio 0
	s_setprio 1
	v_mfma_f32_16x16x32_bf16 v[94:97], v[150:153], v[186:189], v[94:97]
	v_mfma_f32_16x16x32_bf16 v[90:93], v[178:181], v[186:189], v[90:93]
	v_mfma_f32_16x16x32_bf16 v[82:85], v[178:181], v[206:209], v[82:85]
	v_mfma_f32_16x16x32_bf16 v[86:89], v[150:153], v[206:209], v[86:89]
	v_mfma_f32_16x16x32_bf16 v[78:81], v[150:153], v[214:217], v[78:81]
	v_mfma_f32_16x16x32_bf16 v[74:77], v[178:181], v[214:217], v[74:77]
	v_mfma_f32_16x16x32_bf16 v[66:69], v[178:181], v[222:225], v[66:69]
	v_mfma_f32_16x16x32_bf16 v[70:73], v[150:153], v[222:225], v[70:73]
	v_mfma_f32_16x16x32_bf16 v[94:97], v[174:177], v[202:205], v[94:97]
	v_mfma_f32_16x16x32_bf16 v[90:93], v[182:185], v[202:205], v[90:93]
	v_mfma_f32_16x16x32_bf16 v[82:85], v[182:185], v[210:213], v[82:85]
	v_mfma_f32_16x16x32_bf16 v[86:89], v[174:177], v[210:213], v[86:89]
	v_mfma_f32_16x16x32_bf16 v[78:81], v[174:177], v[218:221], v[78:81]
	v_mfma_f32_16x16x32_bf16 v[74:77], v[182:185], v[218:221], v[74:77]
	v_mfma_f32_16x16x32_bf16 v[66:69], v[182:185], v[226:229], v[66:69]
	v_mfma_f32_16x16x32_bf16 v[70:73], v[174:177], v[226:229], v[70:73]
	s_setprio 0
	s_barrier
	s_add_i32 s16, s16, s30
	v_lshl_add_u64 v[190:191], s[64:65], 0, v[154:155]
	s_mov_b32 m0, s16
	ds_read_b128 v[186:189], v200 offset:16384
	ds_read_b128 v[202:205], v200 offset:17408
	ds_read_b128 v[206:209], v200 offset:18432
	ds_read_b128 v[210:213], v200 offset:19456
	ds_read_b128 v[214:217], v200 offset:20480
	ds_read_b128 v[218:221], v200 offset:21504
	ds_read_b128 v[222:225], v200 offset:22528
	ds_read_b128 v[226:229], v200 offset:23552
	global_load_lds_dwordx4 v[190:191], off
	s_add_i32 m0, s16, 0x2000
	s_add_u32 vcc_lo, s64, 0x80000
	v_lshl_add_u64 v[230:231], s[64:65], 0, v[164:165]
	s_addc_u32 vcc_hi, s65, 0
	s_add_i32 s16, s24, s30
	global_load_lds_dwordx4 v[230:231], off
	v_lshl_add_u64 v[232:233], vcc, 0, v[154:155]
	s_mov_b32 m0, s16
	v_lshl_add_u64 v[234:235], s[66:67], 0, v[166:167]
	global_load_lds_dwordx4 v[232:233], off
	v_lshl_add_u64 v[232:233], vcc, 0, v[164:165]
	s_add_i32 m0, s16, 0x2000
	s_nop 0
	global_load_lds_dwordx4 v[232:233], off
	v_lshl_add_u64 v[232:233], s[66:67], 0, v[168:169]
	s_mov_b32 m0, s80
	s_nop 0
	global_load_lds_dwordx4 v[232:233], off
	s_mov_b32 m0, s81
	s_nop 0
	global_load_lds_dwordx4 v[234:235], off
	s_waitcnt vmcnt(8)
	s_waitcnt lgkmcnt(0)
	s_barrier
	s_setprio 1
	s_waitcnt lgkmcnt(0)
	v_mfma_f32_16x16x32_bf16 v[62:65], v[134:137], v[186:189], v[62:65]
	v_mfma_f32_16x16x32_bf16 v[58:61], v[142:145], v[186:189], v[58:61]
	v_mfma_f32_16x16x32_bf16 v[50:53], v[142:145], v[206:209], v[50:53]
	v_mfma_f32_16x16x32_bf16 v[54:57], v[134:137], v[206:209], v[54:57]
	v_mfma_f32_16x16x32_bf16 v[46:49], v[134:137], v[214:217], v[46:49]
	v_mfma_f32_16x16x32_bf16 v[42:45], v[142:145], v[214:217], v[42:45]
	v_mfma_f32_16x16x32_bf16 v[34:37], v[142:145], v[222:225], v[34:37]
	v_mfma_f32_16x16x32_bf16 v[38:41], v[134:137], v[222:225], v[38:41]
	v_mfma_f32_16x16x32_bf16 v[62:65], v[138:141], v[202:205], v[62:65]
	v_mfma_f32_16x16x32_bf16 v[58:61], v[146:149], v[202:205], v[58:61]
	v_mfma_f32_16x16x32_bf16 v[50:53], v[146:149], v[210:213], v[50:53]
	v_mfma_f32_16x16x32_bf16 v[54:57], v[138:141], v[210:213], v[54:57]
	v_mfma_f32_16x16x32_bf16 v[46:49], v[138:141], v[218:221], v[46:49]
	v_mfma_f32_16x16x32_bf16 v[42:45], v[146:149], v[218:221], v[42:45]
	v_mfma_f32_16x16x32_bf16 v[34:37], v[146:149], v[226:229], v[34:37]
	v_mfma_f32_16x16x32_bf16 v[38:41], v[138:141], v[226:229], v[38:41]
	s_setprio 0
	s_setprio 1
	v_mfma_f32_16x16x32_bf16 v[30:33], v[150:153], v[186:189], v[30:33]
	v_mfma_f32_16x16x32_bf16 v[26:29], v[178:181], v[186:189], v[26:29]
	v_mfma_f32_16x16x32_bf16 v[18:21], v[178:181], v[206:209], v[18:21]
	v_mfma_f32_16x16x32_bf16 v[22:25], v[150:153], v[206:209], v[22:25]
	v_mfma_f32_16x16x32_bf16 v[14:17], v[150:153], v[214:217], v[14:17]
	v_mfma_f32_16x16x32_bf16 v[10:13], v[178:181], v[214:217], v[10:13]
	v_mfma_f32_16x16x32_bf16 v[2:5], v[178:181], v[222:225], v[2:5]
	v_mfma_f32_16x16x32_bf16 v[6:9], v[150:153], v[222:225], v[6:9]
	v_mfma_f32_16x16x32_bf16 v[30:33], v[174:177], v[202:205], v[30:33]
	v_mfma_f32_16x16x32_bf16 v[26:29], v[182:185], v[202:205], v[26:29]
	v_mfma_f32_16x16x32_bf16 v[18:21], v[182:185], v[210:213], v[18:21]
	v_mfma_f32_16x16x32_bf16 v[22:25], v[174:177], v[210:213], v[22:25]
	v_mfma_f32_16x16x32_bf16 v[14:17], v[174:177], v[218:221], v[14:17]
	v_mfma_f32_16x16x32_bf16 v[10:13], v[182:185], v[218:221], v[10:13]
	v_mfma_f32_16x16x32_bf16 v[2:5], v[182:185], v[226:229], v[2:5]
	v_mfma_f32_16x16x32_bf16 v[6:9], v[174:177], v[226:229], v[6:9]
	s_setprio 0
	s_barrier
	s_add_i32 s16, 0, 0x18000
	s_add_i32 s24, 0, 0x1c000
	v_add_u32_e32 v146, s16, v197
	v_add_u32_e32 v182, s24, v197
	ds_read_b128 v[134:137], v146
	ds_read_b128 v[138:141], v146 offset:1024
	ds_read_b128 v[142:145], v146 offset:2048
	ds_read_b128 v[146:149], v146 offset:3072
	ds_read_b128 v[150:153], v182
	ds_read_b128 v[174:177], v182 offset:1024
	ds_read_b128 v[178:181], v182 offset:2048
	ds_read_b128 v[182:185], v182 offset:3072
	s_add_u32 s66, s66, 0x80000
	s_addc_u32 s67, s67, 0
	s_mov_b32 m0, s82
	v_lshl_add_u64 v[236:237], s[66:67], 0, v[168:169]
	ds_read_b128 v[186:189], v200 offset:32768
	ds_read_b128 v[202:205], v200 offset:33792
	ds_read_b128 v[206:209], v200 offset:34816
	ds_read_b128 v[210:213], v200 offset:35840
	ds_read_b128 v[214:217], v200 offset:36864
	ds_read_b128 v[218:221], v200 offset:37888
	ds_read_b128 v[222:225], v200 offset:38912
	ds_read_b128 v[226:229], v200 offset:39936
	global_load_lds_dwordx4 v[236:237], off
	v_lshl_add_u64 v[236:237], s[66:67], 0, v[166:167]
	s_mov_b32 m0, s83
	s_nop 0
	global_load_lds_dwordx4 v[236:237], off
	s_waitcnt vmcnt(8)
	s_waitcnt lgkmcnt(0)
	s_barrier
	s_setprio 1
	s_waitcnt lgkmcnt(0)
	v_mfma_f32_16x16x32_bf16 v[126:129], v[134:137], v[186:189], v[126:129]
	v_mfma_f32_16x16x32_bf16 v[122:125], v[142:145], v[186:189], v[122:125]
	v_mfma_f32_16x16x32_bf16 v[114:117], v[142:145], v[206:209], v[114:117]
	v_mfma_f32_16x16x32_bf16 v[118:121], v[134:137], v[206:209], v[118:121]
	v_mfma_f32_16x16x32_bf16 v[110:113], v[134:137], v[214:217], v[110:113]
	v_mfma_f32_16x16x32_bf16 v[106:109], v[142:145], v[214:217], v[106:109]
	v_mfma_f32_16x16x32_bf16 v[98:101], v[142:145], v[222:225], v[98:101]
	v_mfma_f32_16x16x32_bf16 v[102:105], v[134:137], v[222:225], v[102:105]
	v_mfma_f32_16x16x32_bf16 v[126:129], v[138:141], v[202:205], v[126:129]
	v_mfma_f32_16x16x32_bf16 v[122:125], v[146:149], v[202:205], v[122:125]
	v_mfma_f32_16x16x32_bf16 v[114:117], v[146:149], v[210:213], v[114:117]
	v_mfma_f32_16x16x32_bf16 v[118:121], v[138:141], v[210:213], v[118:121]
	v_mfma_f32_16x16x32_bf16 v[110:113], v[138:141], v[218:221], v[110:113]
	v_mfma_f32_16x16x32_bf16 v[106:109], v[146:149], v[218:221], v[106:109]
	v_mfma_f32_16x16x32_bf16 v[98:101], v[146:149], v[226:229], v[98:101]
	v_mfma_f32_16x16x32_bf16 v[102:105], v[138:141], v[226:229], v[102:105]
	s_setprio 0
	s_setprio 1
	v_mfma_f32_16x16x32_bf16 v[94:97], v[150:153], v[186:189], v[94:97]
	v_mfma_f32_16x16x32_bf16 v[90:93], v[178:181], v[186:189], v[90:93]
	v_mfma_f32_16x16x32_bf16 v[82:85], v[178:181], v[206:209], v[82:85]
	v_mfma_f32_16x16x32_bf16 v[86:89], v[150:153], v[206:209], v[86:89]
	v_mfma_f32_16x16x32_bf16 v[78:81], v[150:153], v[214:217], v[78:81]
	v_mfma_f32_16x16x32_bf16 v[74:77], v[178:181], v[214:217], v[74:77]
	v_mfma_f32_16x16x32_bf16 v[66:69], v[178:181], v[222:225], v[66:69]
	v_mfma_f32_16x16x32_bf16 v[70:73], v[150:153], v[222:225], v[70:73]
	v_mfma_f32_16x16x32_bf16 v[94:97], v[174:177], v[202:205], v[94:97]
	v_mfma_f32_16x16x32_bf16 v[90:93], v[182:185], v[202:205], v[90:93]
	v_mfma_f32_16x16x32_bf16 v[82:85], v[182:185], v[210:213], v[82:85]
	v_mfma_f32_16x16x32_bf16 v[86:89], v[174:177], v[210:213], v[86:89]
	v_mfma_f32_16x16x32_bf16 v[78:81], v[174:177], v[218:221], v[78:81]
	v_mfma_f32_16x16x32_bf16 v[74:77], v[182:185], v[218:221], v[74:77]
	v_mfma_f32_16x16x32_bf16 v[66:69], v[182:185], v[226:229], v[66:69]
	v_mfma_f32_16x16x32_bf16 v[70:73], v[174:177], v[226:229], v[70:73]
	s_setprio 0
	s_barrier
	s_add_i32 s16, s16, s30
	v_lshl_add_u64 v[190:191], v[190:191], 0, s[34:35]
	s_mov_b32 m0, s16
	ds_read_b128 v[186:189], v200 offset:49152
	ds_read_b128 v[202:205], v200 offset:50176
	ds_read_b128 v[206:209], v200 offset:51200
	ds_read_b128 v[210:213], v200 offset:52224
	ds_read_b128 v[214:217], v200 offset:53248
	ds_read_b128 v[218:221], v200 offset:54272
	ds_read_b128 v[222:225], v200 offset:55296
	ds_read_b128 v[226:229], v200 offset:56320
	global_load_lds_dwordx4 v[190:191], off
	s_add_i32 m0, s16, 0x2000
	s_add_u32 s64, s64, 0x80080
	v_lshl_add_u64 v[190:191], v[230:231], 0, s[34:35]
	s_addc_u32 s65, s65, 0
	s_add_i32 s16, s24, s30
	global_load_lds_dwordx4 v[190:191], off
	v_lshl_add_u64 v[190:191], s[64:65], 0, v[154:155]
	s_mov_b32 m0, s16
	s_nop 0
	global_load_lds_dwordx4 v[190:191], off
	v_lshl_add_u64 v[190:191], s[64:65], 0, v[164:165]
	s_add_i32 m0, s16, 0x2000
	s_nop 0
	global_load_lds_dwordx4 v[190:191], off
	v_lshl_add_u64 v[190:191], v[232:233], 0, s[34:35]
	s_mov_b32 m0, s84
	s_nop 0
	global_load_lds_dwordx4 v[190:191], off
	v_lshl_add_u64 v[190:191], v[234:235], 0, s[34:35]
	s_mov_b32 m0, s85
	s_nop 0
	global_load_lds_dwordx4 v[190:191], off
	s_waitcnt vmcnt(8)
	s_waitcnt lgkmcnt(0)
	s_barrier
	s_setprio 1
	s_waitcnt lgkmcnt(0)
	v_mfma_f32_16x16x32_bf16 v[62:65], v[134:137], v[186:189], v[62:65]
	v_mfma_f32_16x16x32_bf16 v[58:61], v[142:145], v[186:189], v[58:61]
	v_mfma_f32_16x16x32_bf16 v[50:53], v[142:145], v[206:209], v[50:53]
	v_mfma_f32_16x16x32_bf16 v[54:57], v[134:137], v[206:209], v[54:57]
	v_mfma_f32_16x16x32_bf16 v[46:49], v[134:137], v[214:217], v[46:49]
	v_mfma_f32_16x16x32_bf16 v[42:45], v[142:145], v[214:217], v[42:45]
	v_mfma_f32_16x16x32_bf16 v[34:37], v[142:145], v[222:225], v[34:37]
	v_mfma_f32_16x16x32_bf16 v[38:41], v[134:137], v[222:225], v[38:41]
	v_mfma_f32_16x16x32_bf16 v[62:65], v[138:141], v[202:205], v[62:65]
	v_mfma_f32_16x16x32_bf16 v[58:61], v[146:149], v[202:205], v[58:61]
	v_mfma_f32_16x16x32_bf16 v[50:53], v[146:149], v[210:213], v[50:53]
	v_mfma_f32_16x16x32_bf16 v[54:57], v[138:141], v[210:213], v[54:57]
	v_mfma_f32_16x16x32_bf16 v[46:49], v[138:141], v[218:221], v[46:49]
	v_mfma_f32_16x16x32_bf16 v[42:45], v[146:149], v[218:221], v[42:45]
	v_mfma_f32_16x16x32_bf16 v[34:37], v[146:149], v[226:229], v[34:37]
	v_mfma_f32_16x16x32_bf16 v[38:41], v[138:141], v[226:229], v[38:41]
	s_setprio 0
	s_setprio 1
	v_mfma_f32_16x16x32_bf16 v[30:33], v[150:153], v[186:189], v[30:33]
	v_mfma_f32_16x16x32_bf16 v[26:29], v[178:181], v[186:189], v[26:29]
	v_mfma_f32_16x16x32_bf16 v[18:21], v[178:181], v[206:209], v[18:21]
	v_mfma_f32_16x16x32_bf16 v[22:25], v[150:153], v[206:209], v[22:25]
	v_mfma_f32_16x16x32_bf16 v[14:17], v[150:153], v[214:217], v[14:17]
	v_mfma_f32_16x16x32_bf16 v[10:13], v[178:181], v[214:217], v[10:13]
	v_mfma_f32_16x16x32_bf16 v[2:5], v[178:181], v[222:225], v[2:5]
	v_mfma_f32_16x16x32_bf16 v[6:9], v[150:153], v[222:225], v[6:9]
	v_mfma_f32_16x16x32_bf16 v[30:33], v[174:177], v[202:205], v[30:33]
	v_mfma_f32_16x16x32_bf16 v[26:29], v[182:185], v[202:205], v[26:29]
	v_mfma_f32_16x16x32_bf16 v[18:21], v[182:185], v[210:213], v[18:21]
	v_mfma_f32_16x16x32_bf16 v[22:25], v[174:177], v[210:213], v[22:25]
	v_mfma_f32_16x16x32_bf16 v[14:17], v[174:177], v[218:221], v[14:17]
	v_mfma_f32_16x16x32_bf16 v[10:13], v[182:185], v[218:221], v[10:13]
	v_mfma_f32_16x16x32_bf16 v[2:5], v[182:185], v[226:229], v[2:5]
	v_mfma_f32_16x16x32_bf16 v[6:9], v[174:177], v[226:229], v[6:9]
	s_setprio 0
	s_barrier
	s_add_i32 s97, s97, 2
	s_add_u32 s10, s10, 0x100
	s_addc_u32 s11, s11, 0
	s_cmp_gt_u32 s97, 29
	s_cbranch_scc0 .LBB0_473
	s_and_b64 vcc, exec, s[46:47]
	s_cbranch_vccz .LBB0_476
	s_barrier

.LBB0_623:
	s_add_u32 s8, s52, s0
	s_addc_u32 s9, s53, s1
	s_add_u32 s8, s8, 0x100
	s_addc_u32 s9, s9, 0
	s_add_u32 s55, s76, s0
	s_addc_u32 s78, s77, s1
	s_add_i32 s79, 0, 0x10000
	s_cmpk_eq_i32 s0, 0xf00
	s_cselect_b32 s11, s12, s9
	s_cselect_b32 s10, s13, s8
	s_cselect_b32 s9, s26, s78
	s_cselect_b32 s8, s27, s55
	s_add_i32 s55, 0, 0x14000
	v_add_u32_e32 v148, s79, v204
	v_add_u32_e32 v186, s55, v204
	ds_read_b128 v[136:139], v148
	ds_read_b128 v[140:143], v148 offset:1024
	ds_read_b128 v[144:147], v148 offset:2048
	ds_read_b128 v[148:151], v148 offset:3072
	ds_read_b128 v[152:155], v186
	ds_read_b128 v[156:159], v186 offset:1024
	ds_read_b128 v[160:163], v186 offset:2048
	ds_read_b128 v[186:189], v186 offset:3072
	v_lshl_add_u64 v[230:231], v[132:133], 0, s[0:1]
	s_add_i32 m0, s25, 0xc000
	ds_read_b128 v[190:193], v205
	ds_read_b128 v[194:197], v205 offset:1024
	ds_read_b128 v[206:209], v205 offset:2048
	ds_read_b128 v[210:213], v205 offset:3072
	ds_read_b128 v[214:217], v205 offset:4096
	ds_read_b128 v[218:221], v205 offset:5120
	ds_read_b128 v[222:225], v205 offset:6144
	ds_read_b128 v[226:229], v205 offset:7168
	global_load_lds_dwordx4 v[230:231], off
	v_lshl_add_u64 v[230:231], v[134:135], 0, s[0:1]
	s_add_i32 m0, s25, 0xe000
	s_nop 0
	global_load_lds_dwordx4 v[230:231], off
	s_waitcnt vmcnt(8)
	s_waitcnt lgkmcnt(0)
	s_barrier
	s_setprio 1
	s_waitcnt lgkmcnt(0)
	v_mfma_f32_16x16x32_bf16 v[128:131], v[136:139], v[190:193], v[128:131]
	v_mfma_f32_16x16x32_bf16 v[124:127], v[144:147], v[190:193], v[124:127]
	v_mfma_f32_16x16x32_bf16 v[116:119], v[144:147], v[206:209], v[116:119]
	v_mfma_f32_16x16x32_bf16 v[120:123], v[136:139], v[206:209], v[120:123]
	v_mfma_f32_16x16x32_bf16 v[112:115], v[136:139], v[214:217], v[112:115]
	v_mfma_f32_16x16x32_bf16 v[108:111], v[144:147], v[214:217], v[108:111]
	v_mfma_f32_16x16x32_bf16 v[100:103], v[144:147], v[222:225], v[100:103]
	v_mfma_f32_16x16x32_bf16 v[104:107], v[136:139], v[222:225], v[104:107]
	v_mfma_f32_16x16x32_bf16 v[128:131], v[140:143], v[194:197], v[128:131]
	v_mfma_f32_16x16x32_bf16 v[124:127], v[148:151], v[194:197], v[124:127]
	v_mfma_f32_16x16x32_bf16 v[116:119], v[148:151], v[210:213], v[116:119]
	v_mfma_f32_16x16x32_bf16 v[120:123], v[140:143], v[210:213], v[120:123]
	v_mfma_f32_16x16x32_bf16 v[112:115], v[140:143], v[218:221], v[112:115]
	v_mfma_f32_16x16x32_bf16 v[108:111], v[148:151], v[218:221], v[108:111]
	v_mfma_f32_16x16x32_bf16 v[100:103], v[148:151], v[226:229], v[100:103]
	v_mfma_f32_16x16x32_bf16 v[104:107], v[140:143], v[226:229], v[104:107]
	s_setprio 0
	s_setprio 1
	v_mfma_f32_16x16x32_bf16 v[96:99], v[152:155], v[190:193], v[96:99]
	v_mfma_f32_16x16x32_bf16 v[92:95], v[160:163], v[190:193], v[92:95]
	v_mfma_f32_16x16x32_bf16 v[84:87], v[160:163], v[206:209], v[84:87]
	v_mfma_f32_16x16x32_bf16 v[88:91], v[152:155], v[206:209], v[88:91]
	v_mfma_f32_16x16x32_bf16 v[80:83], v[152:155], v[214:217], v[80:83]
	v_mfma_f32_16x16x32_bf16 v[76:79], v[160:163], v[214:217], v[76:79]
	v_mfma_f32_16x16x32_bf16 v[68:71], v[160:163], v[222:225], v[68:71]
	v_mfma_f32_16x16x32_bf16 v[72:75], v[152:155], v[222:225], v[72:75]
	v_mfma_f32_16x16x32_bf16 v[96:99], v[156:159], v[194:197], v[96:99]
	v_mfma_f32_16x16x32_bf16 v[92:95], v[186:189], v[194:197], v[92:95]
	v_mfma_f32_16x16x32_bf16 v[84:87], v[186:189], v[210:213], v[84:87]
	v_mfma_f32_16x16x32_bf16 v[88:91], v[156:159], v[210:213], v[88:91]
	v_mfma_f32_16x16x32_bf16 v[80:83], v[156:159], v[218:221], v[80:83]
	v_mfma_f32_16x16x32_bf16 v[76:79], v[186:189], v[218:221], v[76:79]
	v_mfma_f32_16x16x32_bf16 v[68:71], v[186:189], v[226:229], v[68:71]
	v_mfma_f32_16x16x32_bf16 v[72:75], v[156:159], v[226:229], v[72:75]
	s_setprio 0
	s_barrier
	s_add_i32 s78, s79, s24
	v_lshl_add_u64 v[230:231], s[8:9], 0, v[170:171]
	s_mov_b32 m0, s78
	ds_read_b128 v[190:193], v205 offset:16384
	ds_read_b128 v[194:197], v205 offset:17408
	ds_read_b128 v[206:209], v205 offset:18432
	ds_read_b128 v[210:213], v205 offset:19456
	ds_read_b128 v[214:217], v205 offset:20480
	ds_read_b128 v[218:221], v205 offset:21504
	ds_read_b128 v[222:225], v205 offset:22528
	ds_read_b128 v[226:229], v205 offset:23552
	global_load_lds_dwordx4 v[230:231], off
	s_add_i32 m0, s78, 0x2000
	s_add_u32 s78, s8, 0x80000
	v_lshl_add_u64 v[232:233], s[8:9], 0, v[174:175]
	s_addc_u32 s79, s9, 0
	s_add_i32 s55, s55, s24
	global_load_lds_dwordx4 v[232:233], off
	v_lshl_add_u64 v[234:235], s[78:79], 0, v[170:171]
	s_mov_b32 m0, s55
	v_lshl_add_u64 v[236:237], s[10:11], 0, v[172:173]
	global_load_lds_dwordx4 v[234:235], off
	v_lshl_add_u64 v[234:235], s[78:79], 0, v[174:175]
	s_add_i32 m0, s55, 0x2000
	s_nop 0
	global_load_lds_dwordx4 v[234:235], off
	v_lshl_add_u64 v[234:235], s[10:11], 0, v[168:169]
	s_mov_b32 m0, s25
	s_nop 0
	global_load_lds_dwordx4 v[234:235], off
	s_mov_b32 m0, s30
	s_nop 0
	global_load_lds_dwordx4 v[236:237], off
	s_waitcnt vmcnt(8)
	s_waitcnt lgkmcnt(0)
	s_barrier
	s_setprio 1
	s_waitcnt lgkmcnt(0)
	v_mfma_f32_16x16x32_bf16 v[64:67], v[136:139], v[190:193], v[64:67]
	v_mfma_f32_16x16x32_bf16 v[60:63], v[144:147], v[190:193], v[60:63]
	v_mfma_f32_16x16x32_bf16 v[52:55], v[144:147], v[206:209], v[52:55]
	v_mfma_f32_16x16x32_bf16 v[56:59], v[136:139], v[206:209], v[56:59]
	v_mfma_f32_16x16x32_bf16 v[48:51], v[136:139], v[214:217], v[48:51]
	v_mfma_f32_16x16x32_bf16 v[44:47], v[144:147], v[214:217], v[44:47]
	v_mfma_f32_16x16x32_bf16 v[36:39], v[144:147], v[222:225], v[36:39]
	v_mfma_f32_16x16x32_bf16 v[40:43], v[136:139], v[222:225], v[40:43]
	v_mfma_f32_16x16x32_bf16 v[64:67], v[140:143], v[194:197], v[64:67]
	v_mfma_f32_16x16x32_bf16 v[60:63], v[148:151], v[194:197], v[60:63]
	v_mfma_f32_16x16x32_bf16 v[52:55], v[148:151], v[210:213], v[52:55]
	v_mfma_f32_16x16x32_bf16 v[56:59], v[140:143], v[210:213], v[56:59]
	v_mfma_f32_16x16x32_bf16 v[48:51], v[140:143], v[218:221], v[48:51]
	v_mfma_f32_16x16x32_bf16 v[44:47], v[148:151], v[218:221], v[44:47]
	v_mfma_f32_16x16x32_bf16 v[36:39], v[148:151], v[226:229], v[36:39]
	v_mfma_f32_16x16x32_bf16 v[40:43], v[140:143], v[226:229], v[40:43]
	s_setprio 0
	s_setprio 1
	v_mfma_f32_16x16x32_bf16 v[32:35], v[152:155], v[190:193], v[32:35]
	v_mfma_f32_16x16x32_bf16 v[28:31], v[160:163], v[190:193], v[28:31]
	v_mfma_f32_16x16x32_bf16 v[20:23], v[160:163], v[206:209], v[20:23]
	v_mfma_f32_16x16x32_bf16 v[24:27], v[152:155], v[206:209], v[24:27]
	v_mfma_f32_16x16x32_bf16 v[16:19], v[152:155], v[214:217], v[16:19]
	v_mfma_f32_16x16x32_bf16 v[12:15], v[160:163], v[214:217], v[12:15]
	v_mfma_f32_16x16x32_bf16 v[4:7], v[160:163], v[222:225], v[4:7]
	v_mfma_f32_16x16x32_bf16 v[8:11], v[152:155], v[222:225], v[8:11]
	v_mfma_f32_16x16x32_bf16 v[32:35], v[156:159], v[194:197], v[32:35]
	v_mfma_f32_16x16x32_bf16 v[28:31], v[186:189], v[194:197], v[28:31]
	v_mfma_f32_16x16x32_bf16 v[20:23], v[186:189], v[210:213], v[20:23]
	v_mfma_f32_16x16x32_bf16 v[24:27], v[156:159], v[210:213], v[24:27]
	v_mfma_f32_16x16x32_bf16 v[16:19], v[156:159], v[218:221], v[16:19]
	v_mfma_f32_16x16x32_bf16 v[12:15], v[186:189], v[218:221], v[12:15]
	v_mfma_f32_16x16x32_bf16 v[4:7], v[186:189], v[226:229], v[4:7]
	v_mfma_f32_16x16x32_bf16 v[8:11], v[156:159], v[226:229], v[8:11]
	s_setprio 0
	s_barrier
	s_add_i32 s55, 0, 0x18000
	s_add_i32 s78, 0, 0x1c000
	v_add_u32_e32 v148, s55, v204
	v_add_u32_e32 v186, s78, v204
	ds_read_b128 v[136:139], v148
	ds_read_b128 v[140:143], v148 offset:1024
	ds_read_b128 v[144:147], v148 offset:2048
	ds_read_b128 v[148:151], v148 offset:3072
	ds_read_b128 v[152:155], v186
	ds_read_b128 v[156:159], v186 offset:1024
	ds_read_b128 v[160:163], v186 offset:2048
	ds_read_b128 v[186:189], v186 offset:3072
	s_add_u32 s10, s10, 0x80000
	s_addc_u32 s11, s11, 0
	s_mov_b32 m0, s31
	v_lshl_add_u64 v[238:239], s[10:11], 0, v[168:169]
	ds_read_b128 v[190:193], v205 offset:32768
	ds_read_b128 v[194:197], v205 offset:33792
	ds_read_b128 v[206:209], v205 offset:34816
	ds_read_b128 v[210:213], v205 offset:35840
	ds_read_b128 v[214:217], v205 offset:36864
	ds_read_b128 v[218:221], v205 offset:37888
	ds_read_b128 v[222:225], v205 offset:38912
	ds_read_b128 v[226:229], v205 offset:39936
	global_load_lds_dwordx4 v[238:239], off
	v_lshl_add_u64 v[238:239], s[10:11], 0, v[172:173]
	s_mov_b32 m0, s36
	s_nop 0
	global_load_lds_dwordx4 v[238:239], off
	s_waitcnt vmcnt(8)
	s_waitcnt lgkmcnt(0)
	s_barrier
	s_setprio 1
	s_waitcnt lgkmcnt(0)
	v_mfma_f32_16x16x32_bf16 v[128:131], v[136:139], v[190:193], v[128:131]
	v_mfma_f32_16x16x32_bf16 v[124:127], v[144:147], v[190:193], v[124:127]
	v_mfma_f32_16x16x32_bf16 v[116:119], v[144:147], v[206:209], v[116:119]
	v_mfma_f32_16x16x32_bf16 v[120:123], v[136:139], v[206:209], v[120:123]
	v_mfma_f32_16x16x32_bf16 v[112:115], v[136:139], v[214:217], v[112:115]
	v_mfma_f32_16x16x32_bf16 v[108:111], v[144:147], v[214:217], v[108:111]
	v_mfma_f32_16x16x32_bf16 v[100:103], v[144:147], v[222:225], v[100:103]
	v_mfma_f32_16x16x32_bf16 v[104:107], v[136:139], v[222:225], v[104:107]
	v_mfma_f32_16x16x32_bf16 v[128:131], v[140:143], v[194:197], v[128:131]
	v_mfma_f32_16x16x32_bf16 v[124:127], v[148:151], v[194:197], v[124:127]
	v_mfma_f32_16x16x32_bf16 v[116:119], v[148:151], v[210:213], v[116:119]
	v_mfma_f32_16x16x32_bf16 v[120:123], v[140:143], v[210:213], v[120:123]
	v_mfma_f32_16x16x32_bf16 v[112:115], v[140:143], v[218:221], v[112:115]
	v_mfma_f32_16x16x32_bf16 v[108:111], v[148:151], v[218:221], v[108:111]
	v_mfma_f32_16x16x32_bf16 v[100:103], v[148:151], v[226:229], v[100:103]
	v_mfma_f32_16x16x32_bf16 v[104:107], v[140:143], v[226:229], v[104:107]
	s_setprio 0
	s_setprio 1
	v_mfma_f32_16x16x32_bf16 v[96:99], v[152:155], v[190:193], v[96:99]
	v_mfma_f32_16x16x32_bf16 v[92:95], v[160:163], v[190:193], v[92:95]
	v_mfma_f32_16x16x32_bf16 v[84:87], v[160:163], v[206:209], v[84:87]
	v_mfma_f32_16x16x32_bf16 v[88:91], v[152:155], v[206:209], v[88:91]
	v_mfma_f32_16x16x32_bf16 v[80:83], v[152:155], v[214:217], v[80:83]
	v_mfma_f32_16x16x32_bf16 v[76:79], v[160:163], v[214:217], v[76:79]
	v_mfma_f32_16x16x32_bf16 v[68:71], v[160:163], v[222:225], v[68:71]
	v_mfma_f32_16x16x32_bf16 v[72:75], v[152:155], v[222:225], v[72:75]
	v_mfma_f32_16x16x32_bf16 v[96:99], v[156:159], v[194:197], v[96:99]
	v_mfma_f32_16x16x32_bf16 v[92:95], v[186:189], v[194:197], v[92:95]
	v_mfma_f32_16x16x32_bf16 v[84:87], v[186:189], v[210:213], v[84:87]
	v_mfma_f32_16x16x32_bf16 v[88:91], v[156:159], v[210:213], v[88:91]
	v_mfma_f32_16x16x32_bf16 v[80:83], v[156:159], v[218:221], v[80:83]
	v_mfma_f32_16x16x32_bf16 v[76:79], v[186:189], v[218:221], v[76:79]
	v_mfma_f32_16x16x32_bf16 v[68:71], v[186:189], v[226:229], v[68:71]
	v_mfma_f32_16x16x32_bf16 v[72:75], v[156:159], v[226:229], v[72:75]
	s_setprio 0
	s_barrier
	s_add_i32 s10, s55, s24
	v_lshl_add_u64 v[230:231], v[230:231], 0, s[28:29]
	s_mov_b32 m0, s10
	ds_read_b128 v[190:193], v205 offset:49152
	ds_read_b128 v[194:197], v205 offset:50176
	ds_read_b128 v[206:209], v205 offset:51200
	ds_read_b128 v[210:213], v205 offset:52224
	ds_read_b128 v[214:217], v205 offset:53248
	ds_read_b128 v[218:221], v205 offset:54272
	ds_read_b128 v[222:225], v205 offset:55296
	ds_read_b128 v[226:229], v205 offset:56320
	global_load_lds_dwordx4 v[230:231], off
	s_add_i32 m0, s10, 0x2000
	s_add_u32 s8, s8, 0x80080
	v_lshl_add_u64 v[230:231], v[232:233], 0, s[28:29]
	s_addc_u32 s9, s9, 0
	s_add_i32 s10, s78, s24
	global_load_lds_dwordx4 v[230:231], off
	v_lshl_add_u64 v[230:231], s[8:9], 0, v[170:171]
	s_mov_b32 m0, s10
	s_nop 0
	global_load_lds_dwordx4 v[230:231], off
	v_lshl_add_u64 v[230:231], s[8:9], 0, v[174:175]
	s_add_i32 m0, s10, 0x2000
	s_nop 0
	global_load_lds_dwordx4 v[230:231], off
	v_lshl_add_u64 v[230:231], v[234:235], 0, s[28:29]
	s_mov_b32 m0, s45
	s_nop 0
	global_load_lds_dwordx4 v[230:231], off
	v_lshl_add_u64 v[230:231], v[236:237], 0, s[28:29]
	s_mov_b32 m0, s60
	s_nop 0
	global_load_lds_dwordx4 v[230:231], off
	s_waitcnt vmcnt(8)
	s_waitcnt lgkmcnt(0)
	s_barrier
	s_setprio 1
	s_waitcnt lgkmcnt(0)
	v_mfma_f32_16x16x32_bf16 v[64:67], v[136:139], v[190:193], v[64:67]
	v_mfma_f32_16x16x32_bf16 v[60:63], v[144:147], v[190:193], v[60:63]
	v_mfma_f32_16x16x32_bf16 v[52:55], v[144:147], v[206:209], v[52:55]
	v_mfma_f32_16x16x32_bf16 v[56:59], v[136:139], v[206:209], v[56:59]
	v_mfma_f32_16x16x32_bf16 v[48:51], v[136:139], v[214:217], v[48:51]
	v_mfma_f32_16x16x32_bf16 v[44:47], v[144:147], v[214:217], v[44:47]
	v_mfma_f32_16x16x32_bf16 v[36:39], v[144:147], v[222:225], v[36:39]
	v_mfma_f32_16x16x32_bf16 v[40:43], v[136:139], v[222:225], v[40:43]
	v_mfma_f32_16x16x32_bf16 v[64:67], v[140:143], v[194:197], v[64:67]
	v_mfma_f32_16x16x32_bf16 v[60:63], v[148:151], v[194:197], v[60:63]
	v_mfma_f32_16x16x32_bf16 v[52:55], v[148:151], v[210:213], v[52:55]
	v_mfma_f32_16x16x32_bf16 v[56:59], v[140:143], v[210:213], v[56:59]
	v_mfma_f32_16x16x32_bf16 v[48:51], v[140:143], v[218:221], v[48:51]
	v_mfma_f32_16x16x32_bf16 v[44:47], v[148:151], v[218:221], v[44:47]
	v_mfma_f32_16x16x32_bf16 v[36:39], v[148:151], v[226:229], v[36:39]
	v_mfma_f32_16x16x32_bf16 v[40:43], v[140:143], v[226:229], v[40:43]
	s_setprio 0
	s_setprio 1
	v_mfma_f32_16x16x32_bf16 v[32:35], v[152:155], v[190:193], v[32:35]
	v_mfma_f32_16x16x32_bf16 v[28:31], v[160:163], v[190:193], v[28:31]
	v_mfma_f32_16x16x32_bf16 v[20:23], v[160:163], v[206:209], v[20:23]
	v_mfma_f32_16x16x32_bf16 v[24:27], v[152:155], v[206:209], v[24:27]
	v_mfma_f32_16x16x32_bf16 v[16:19], v[152:155], v[214:217], v[16:19]
	v_mfma_f32_16x16x32_bf16 v[12:15], v[160:163], v[214:217], v[12:15]
	v_mfma_f32_16x16x32_bf16 v[4:7], v[160:163], v[222:225], v[4:7]
	v_mfma_f32_16x16x32_bf16 v[8:11], v[152:155], v[222:225], v[8:11]
	v_mfma_f32_16x16x32_bf16 v[32:35], v[156:159], v[194:197], v[32:35]
	v_mfma_f32_16x16x32_bf16 v[28:31], v[186:189], v[194:197], v[28:31]
	v_mfma_f32_16x16x32_bf16 v[20:23], v[186:189], v[210:213], v[20:23]
	v_mfma_f32_16x16x32_bf16 v[24:27], v[156:159], v[210:213], v[24:27]
	v_mfma_f32_16x16x32_bf16 v[16:19], v[156:159], v[218:221], v[16:19]
	v_mfma_f32_16x16x32_bf16 v[12:15], v[186:189], v[218:221], v[12:15]
	v_mfma_f32_16x16x32_bf16 v[4:7], v[186:189], v[226:229], v[4:7]
	v_mfma_f32_16x16x32_bf16 v[8:11], v[156:159], v[226:229], v[8:11]
	s_setprio 0
	s_barrier
	s_add_i32 s43, s43, 2
	s_add_u32 s0, s0, 0x100
	s_addc_u32 s1, s1, 0
	s_cmp_gt_u32 s43, 29
	s_cbranch_scc0 .LBB0_623
	s_and_b64 vcc, exec, s[50:51]
	s_cbranch_vccz .LBB0_626
	s_barrier

.LBB0_866:
	s_add_u32 s24, s34, s10
	s_addc_u32 s25, s35, s11
	s_add_u32 s24, s24, 0x100
	s_addc_u32 s25, s25, 0
	s_add_u32 s67, s60, s10
	s_addc_u32 s74, s61, s11
	s_add_i32 s75, 0, 0x10000
	s_cmpk_eq_i32 s10, 0xf00
	s_cselect_b32 s31, s27, s25
	s_cselect_b32 s30, s62, s24
	s_cselect_b32 s25, s15, s74
	s_cselect_b32 s24, s63, s67
	s_add_i32 s67, 0, 0x14000
	v_add_u32_e32 v148, s75, v189
	v_add_u32_e32 v178, s67, v189
	ds_read_b128 v[136:139], v148
	ds_read_b128 v[140:143], v148 offset:1024
	ds_read_b128 v[144:147], v148 offset:2048
	ds_read_b128 v[148:151], v148 offset:3072
	ds_read_b128 v[152:155], v178
	ds_read_b128 v[170:173], v178 offset:1024
	ds_read_b128 v[174:177], v178 offset:2048
	ds_read_b128 v[178:181], v178 offset:3072
	v_lshl_add_u64 v[186:187], v[132:133], 0, s[10:11]
	s_add_i32 m0, s48, 0xc000
	ds_read_b128 v[182:185], v191
	ds_read_b128 v[192:195], v191 offset:1024
	ds_read_b128 v[204:207], v191 offset:2048
	ds_read_b128 v[208:211], v191 offset:3072
	ds_read_b128 v[212:215], v191 offset:4096
	ds_read_b128 v[216:219], v191 offset:5120
	ds_read_b128 v[220:223], v191 offset:6144
	ds_read_b128 v[224:227], v191 offset:7168
	global_load_lds_dwordx4 v[186:187], off
	v_lshl_add_u64 v[186:187], v[134:135], 0, s[10:11]
	s_add_i32 m0, s48, 0xe000
	s_nop 0
	global_load_lds_dwordx4 v[186:187], off
	s_waitcnt vmcnt(8)
	s_waitcnt lgkmcnt(0)
	s_barrier
	s_setprio 1
	s_waitcnt lgkmcnt(0)
	v_mfma_f32_16x16x32_bf16 v[128:131], v[136:139], v[182:185], v[128:131]
	v_mfma_f32_16x16x32_bf16 v[124:127], v[144:147], v[182:185], v[124:127]
	v_mfma_f32_16x16x32_bf16 v[116:119], v[144:147], v[204:207], v[116:119]
	v_mfma_f32_16x16x32_bf16 v[120:123], v[136:139], v[204:207], v[120:123]
	v_mfma_f32_16x16x32_bf16 v[112:115], v[136:139], v[212:215], v[112:115]
	v_mfma_f32_16x16x32_bf16 v[108:111], v[144:147], v[212:215], v[108:111]
	v_mfma_f32_16x16x32_bf16 v[100:103], v[144:147], v[220:223], v[100:103]
	v_mfma_f32_16x16x32_bf16 v[104:107], v[136:139], v[220:223], v[104:107]
	v_mfma_f32_16x16x32_bf16 v[128:131], v[140:143], v[192:195], v[128:131]
	v_mfma_f32_16x16x32_bf16 v[124:127], v[148:151], v[192:195], v[124:127]
	v_mfma_f32_16x16x32_bf16 v[116:119], v[148:151], v[208:211], v[116:119]
	v_mfma_f32_16x16x32_bf16 v[120:123], v[140:143], v[208:211], v[120:123]
	v_mfma_f32_16x16x32_bf16 v[112:115], v[140:143], v[216:219], v[112:115]
	v_mfma_f32_16x16x32_bf16 v[108:111], v[148:151], v[216:219], v[108:111]
	v_mfma_f32_16x16x32_bf16 v[100:103], v[148:151], v[224:227], v[100:103]
	v_mfma_f32_16x16x32_bf16 v[104:107], v[140:143], v[224:227], v[104:107]
	s_setprio 0
	s_setprio 1
	v_mfma_f32_16x16x32_bf16 v[96:99], v[152:155], v[182:185], v[96:99]
	v_mfma_f32_16x16x32_bf16 v[92:95], v[174:177], v[182:185], v[92:95]
	v_mfma_f32_16x16x32_bf16 v[84:87], v[174:177], v[204:207], v[84:87]
	v_mfma_f32_16x16x32_bf16 v[88:91], v[152:155], v[204:207], v[88:91]
	v_mfma_f32_16x16x32_bf16 v[80:83], v[152:155], v[212:215], v[80:83]
	v_mfma_f32_16x16x32_bf16 v[76:79], v[174:177], v[212:215], v[76:79]
	v_mfma_f32_16x16x32_bf16 v[68:71], v[174:177], v[220:223], v[68:71]
	v_mfma_f32_16x16x32_bf16 v[72:75], v[152:155], v[220:223], v[72:75]
	v_mfma_f32_16x16x32_bf16 v[96:99], v[170:173], v[192:195], v[96:99]
	v_mfma_f32_16x16x32_bf16 v[92:95], v[178:181], v[192:195], v[92:95]
	v_mfma_f32_16x16x32_bf16 v[84:87], v[178:181], v[208:211], v[84:87]
	v_mfma_f32_16x16x32_bf16 v[88:91], v[170:173], v[208:211], v[88:91]
	v_mfma_f32_16x16x32_bf16 v[80:83], v[170:173], v[216:219], v[80:83]
	v_mfma_f32_16x16x32_bf16 v[76:79], v[178:181], v[216:219], v[76:79]
	v_mfma_f32_16x16x32_bf16 v[68:71], v[178:181], v[224:227], v[68:71]
	v_mfma_f32_16x16x32_bf16 v[72:75], v[170:173], v[224:227], v[72:75]
	s_setprio 0
	s_barrier
	s_add_i32 s74, s75, s47
	v_lshl_add_u64 v[186:187], s[24:25], 0, v[2:3]
	s_mov_b32 m0, s74
	ds_read_b128 v[182:185], v191 offset:16384
	ds_read_b128 v[192:195], v191 offset:17408
	ds_read_b128 v[204:207], v191 offset:18432
	ds_read_b128 v[208:211], v191 offset:19456
	ds_read_b128 v[212:215], v191 offset:20480
	ds_read_b128 v[216:219], v191 offset:21504
	ds_read_b128 v[220:223], v191 offset:22528
	ds_read_b128 v[224:227], v191 offset:23552
	global_load_lds_dwordx4 v[186:187], off
	s_add_i32 m0, s74, 0x2000
	s_add_u32 s74, s24, 0x80000
	v_lshl_add_u64 v[196:197], s[24:25], 0, v[156:157]
	s_addc_u32 s75, s25, 0
	s_add_i32 s67, s67, s47
	global_load_lds_dwordx4 v[196:197], off
	v_lshl_add_u64 v[228:229], s[74:75], 0, v[2:3]
	s_mov_b32 m0, s67
	v_lshl_add_u64 v[230:231], s[30:31], 0, v[158:159]
	global_load_lds_dwordx4 v[228:229], off
	v_lshl_add_u64 v[228:229], s[74:75], 0, v[156:157]
	s_add_i32 m0, s67, 0x2000
	s_nop 0
	global_load_lds_dwordx4 v[228:229], off
	v_lshl_add_u64 v[228:229], s[30:31], 0, v[160:161]
	s_mov_b32 m0, s48
	s_nop 0
	global_load_lds_dwordx4 v[228:229], off
	s_mov_b32 m0, s49
	s_nop 0
	global_load_lds_dwordx4 v[230:231], off
	s_waitcnt vmcnt(8)
	s_waitcnt lgkmcnt(0)
	s_barrier
	s_setprio 1
	s_waitcnt lgkmcnt(0)
	v_mfma_f32_16x16x32_bf16 v[64:67], v[136:139], v[182:185], v[64:67]
	v_mfma_f32_16x16x32_bf16 v[60:63], v[144:147], v[182:185], v[60:63]
	v_mfma_f32_16x16x32_bf16 v[52:55], v[144:147], v[204:207], v[52:55]
	v_mfma_f32_16x16x32_bf16 v[56:59], v[136:139], v[204:207], v[56:59]
	v_mfma_f32_16x16x32_bf16 v[48:51], v[136:139], v[212:215], v[48:51]
	v_mfma_f32_16x16x32_bf16 v[44:47], v[144:147], v[212:215], v[44:47]
	v_mfma_f32_16x16x32_bf16 v[36:39], v[144:147], v[220:223], v[36:39]
	v_mfma_f32_16x16x32_bf16 v[40:43], v[136:139], v[220:223], v[40:43]
	v_mfma_f32_16x16x32_bf16 v[64:67], v[140:143], v[192:195], v[64:67]
	v_mfma_f32_16x16x32_bf16 v[60:63], v[148:151], v[192:195], v[60:63]
	v_mfma_f32_16x16x32_bf16 v[52:55], v[148:151], v[208:211], v[52:55]
	v_mfma_f32_16x16x32_bf16 v[56:59], v[140:143], v[208:211], v[56:59]
	v_mfma_f32_16x16x32_bf16 v[48:51], v[140:143], v[216:219], v[48:51]
	v_mfma_f32_16x16x32_bf16 v[44:47], v[148:151], v[216:219], v[44:47]
	v_mfma_f32_16x16x32_bf16 v[36:39], v[148:151], v[224:227], v[36:39]
	v_mfma_f32_16x16x32_bf16 v[40:43], v[140:143], v[224:227], v[40:43]
	s_setprio 0
	s_setprio 1
	v_mfma_f32_16x16x32_bf16 v[32:35], v[152:155], v[182:185], v[32:35]
	v_mfma_f32_16x16x32_bf16 v[28:31], v[174:177], v[182:185], v[28:31]
	v_mfma_f32_16x16x32_bf16 v[20:23], v[174:177], v[204:207], v[20:23]
	v_mfma_f32_16x16x32_bf16 v[24:27], v[152:155], v[204:207], v[24:27]
	v_mfma_f32_16x16x32_bf16 v[16:19], v[152:155], v[212:215], v[16:19]
	v_mfma_f32_16x16x32_bf16 v[12:15], v[174:177], v[212:215], v[12:15]
	v_mfma_f32_16x16x32_bf16 v[4:7], v[174:177], v[220:223], v[4:7]
	v_mfma_f32_16x16x32_bf16 v[8:11], v[152:155], v[220:223], v[8:11]
	v_mfma_f32_16x16x32_bf16 v[32:35], v[170:173], v[192:195], v[32:35]
	v_mfma_f32_16x16x32_bf16 v[28:31], v[178:181], v[192:195], v[28:31]
	v_mfma_f32_16x16x32_bf16 v[20:23], v[178:181], v[208:211], v[20:23]
	v_mfma_f32_16x16x32_bf16 v[24:27], v[170:173], v[208:211], v[24:27]
	v_mfma_f32_16x16x32_bf16 v[16:19], v[170:173], v[216:219], v[16:19]
	v_mfma_f32_16x16x32_bf16 v[12:15], v[178:181], v[216:219], v[12:15]
	v_mfma_f32_16x16x32_bf16 v[4:7], v[178:181], v[224:227], v[4:7]
	v_mfma_f32_16x16x32_bf16 v[8:11], v[170:173], v[224:227], v[8:11]
	s_setprio 0
	s_barrier
	s_add_i32 s67, 0, 0x18000
	s_add_i32 s74, 0, 0x1c000
	v_add_u32_e32 v148, s67, v189
	v_add_u32_e32 v178, s74, v189
	ds_read_b128 v[136:139], v148
	ds_read_b128 v[140:143], v148 offset:1024
	ds_read_b128 v[144:147], v148 offset:2048
	ds_read_b128 v[148:151], v148 offset:3072
	ds_read_b128 v[152:155], v178
	ds_read_b128 v[170:173], v178 offset:1024
	ds_read_b128 v[174:177], v178 offset:2048
	ds_read_b128 v[178:181], v178 offset:3072
	s_add_u32 s30, s30, 0x80000
	s_addc_u32 s31, s31, 0
	s_mov_b32 m0, s50
	v_lshl_add_u64 v[232:233], s[30:31], 0, v[160:161]
	ds_read_b128 v[182:185], v191 offset:32768
	ds_read_b128 v[192:195], v191 offset:33792
	ds_read_b128 v[204:207], v191 offset:34816
	ds_read_b128 v[208:211], v191 offset:35840
	ds_read_b128 v[212:215], v191 offset:36864
	ds_read_b128 v[216:219], v191 offset:37888
	ds_read_b128 v[220:223], v191 offset:38912
	ds_read_b128 v[224:227], v191 offset:39936
	global_load_lds_dwordx4 v[232:233], off
	v_lshl_add_u64 v[232:233], s[30:31], 0, v[158:159]
	s_mov_b32 m0, s51
	s_nop 0
	global_load_lds_dwordx4 v[232:233], off
	s_waitcnt vmcnt(8)
	s_waitcnt lgkmcnt(0)
	s_barrier
	s_setprio 1
	s_waitcnt lgkmcnt(0)
	v_mfma_f32_16x16x32_bf16 v[128:131], v[136:139], v[182:185], v[128:131]
	v_mfma_f32_16x16x32_bf16 v[124:127], v[144:147], v[182:185], v[124:127]
	v_mfma_f32_16x16x32_bf16 v[116:119], v[144:147], v[204:207], v[116:119]
	v_mfma_f32_16x16x32_bf16 v[120:123], v[136:139], v[204:207], v[120:123]
	v_mfma_f32_16x16x32_bf16 v[112:115], v[136:139], v[212:215], v[112:115]
	v_mfma_f32_16x16x32_bf16 v[108:111], v[144:147], v[212:215], v[108:111]
	v_mfma_f32_16x16x32_bf16 v[100:103], v[144:147], v[220:223], v[100:103]
	v_mfma_f32_16x16x32_bf16 v[104:107], v[136:139], v[220:223], v[104:107]
	v_mfma_f32_16x16x32_bf16 v[128:131], v[140:143], v[192:195], v[128:131]
	v_mfma_f32_16x16x32_bf16 v[124:127], v[148:151], v[192:195], v[124:127]
	v_mfma_f32_16x16x32_bf16 v[116:119], v[148:151], v[208:211], v[116:119]
	v_mfma_f32_16x16x32_bf16 v[120:123], v[140:143], v[208:211], v[120:123]
	v_mfma_f32_16x16x32_bf16 v[112:115], v[140:143], v[216:219], v[112:115]
	v_mfma_f32_16x16x32_bf16 v[108:111], v[148:151], v[216:219], v[108:111]
	v_mfma_f32_16x16x32_bf16 v[100:103], v[148:151], v[224:227], v[100:103]
	v_mfma_f32_16x16x32_bf16 v[104:107], v[140:143], v[224:227], v[104:107]
	s_setprio 0
	s_setprio 1
	v_mfma_f32_16x16x32_bf16 v[96:99], v[152:155], v[182:185], v[96:99]
	v_mfma_f32_16x16x32_bf16 v[92:95], v[174:177], v[182:185], v[92:95]
	v_mfma_f32_16x16x32_bf16 v[84:87], v[174:177], v[204:207], v[84:87]
	v_mfma_f32_16x16x32_bf16 v[88:91], v[152:155], v[204:207], v[88:91]
	v_mfma_f32_16x16x32_bf16 v[80:83], v[152:155], v[212:215], v[80:83]
	v_mfma_f32_16x16x32_bf16 v[76:79], v[174:177], v[212:215], v[76:79]
	v_mfma_f32_16x16x32_bf16 v[68:71], v[174:177], v[220:223], v[68:71]
	v_mfma_f32_16x16x32_bf16 v[72:75], v[152:155], v[220:223], v[72:75]
	v_mfma_f32_16x16x32_bf16 v[96:99], v[170:173], v[192:195], v[96:99]
	v_mfma_f32_16x16x32_bf16 v[92:95], v[178:181], v[192:195], v[92:95]
	v_mfma_f32_16x16x32_bf16 v[84:87], v[178:181], v[208:211], v[84:87]
	v_mfma_f32_16x16x32_bf16 v[88:91], v[170:173], v[208:211], v[88:91]
	v_mfma_f32_16x16x32_bf16 v[80:83], v[170:173], v[216:219], v[80:83]
	v_mfma_f32_16x16x32_bf16 v[76:79], v[178:181], v[216:219], v[76:79]
	v_mfma_f32_16x16x32_bf16 v[68:71], v[178:181], v[224:227], v[68:71]
	v_mfma_f32_16x16x32_bf16 v[72:75], v[170:173], v[224:227], v[72:75]
	s_setprio 0
	s_barrier
	s_add_i32 s30, s67, s47
	v_lshl_add_u64 v[186:187], v[186:187], 0, s[28:29]
	s_mov_b32 m0, s30
	ds_read_b128 v[182:185], v191 offset:49152
	ds_read_b128 v[192:195], v191 offset:50176
	ds_read_b128 v[204:207], v191 offset:51200
	ds_read_b128 v[208:211], v191 offset:52224
	ds_read_b128 v[212:215], v191 offset:53248
	ds_read_b128 v[216:219], v191 offset:54272
	ds_read_b128 v[220:223], v191 offset:55296
	ds_read_b128 v[224:227], v191 offset:56320
	global_load_lds_dwordx4 v[186:187], off
	s_add_i32 m0, s30, 0x2000
	s_add_u32 s24, s24, 0x80080
	v_lshl_add_u64 v[186:187], v[196:197], 0, s[28:29]
	s_addc_u32 s25, s25, 0
	s_add_i32 s30, s74, s47
	global_load_lds_dwordx4 v[186:187], off
	v_lshl_add_u64 v[186:187], s[24:25], 0, v[2:3]
	s_mov_b32 m0, s30
	s_nop 0
	global_load_lds_dwordx4 v[186:187], off
	v_lshl_add_u64 v[186:187], s[24:25], 0, v[156:157]
	s_add_i32 m0, s30, 0x2000
	s_nop 0
	global_load_lds_dwordx4 v[186:187], off
	v_lshl_add_u64 v[186:187], v[228:229], 0, s[28:29]
	s_mov_b32 m0, s52
	s_nop 0
	global_load_lds_dwordx4 v[186:187], off
	v_lshl_add_u64 v[186:187], v[230:231], 0, s[28:29]
	s_mov_b32 m0, s53
	s_nop 0
	global_load_lds_dwordx4 v[186:187], off
	s_waitcnt vmcnt(8)
	s_waitcnt lgkmcnt(0)
	s_barrier
	s_setprio 1
	s_waitcnt lgkmcnt(0)
	v_mfma_f32_16x16x32_bf16 v[64:67], v[136:139], v[182:185], v[64:67]
	v_mfma_f32_16x16x32_bf16 v[60:63], v[144:147], v[182:185], v[60:63]
	v_mfma_f32_16x16x32_bf16 v[52:55], v[144:147], v[204:207], v[52:55]
	v_mfma_f32_16x16x32_bf16 v[56:59], v[136:139], v[204:207], v[56:59]
	v_mfma_f32_16x16x32_bf16 v[48:51], v[136:139], v[212:215], v[48:51]
	v_mfma_f32_16x16x32_bf16 v[44:47], v[144:147], v[212:215], v[44:47]
	v_mfma_f32_16x16x32_bf16 v[36:39], v[144:147], v[220:223], v[36:39]
	v_mfma_f32_16x16x32_bf16 v[40:43], v[136:139], v[220:223], v[40:43]
	v_mfma_f32_16x16x32_bf16 v[64:67], v[140:143], v[192:195], v[64:67]
	v_mfma_f32_16x16x32_bf16 v[60:63], v[148:151], v[192:195], v[60:63]
	v_mfma_f32_16x16x32_bf16 v[52:55], v[148:151], v[208:211], v[52:55]
	v_mfma_f32_16x16x32_bf16 v[56:59], v[140:143], v[208:211], v[56:59]
	v_mfma_f32_16x16x32_bf16 v[48:51], v[140:143], v[216:219], v[48:51]
	v_mfma_f32_16x16x32_bf16 v[44:47], v[148:151], v[216:219], v[44:47]
	v_mfma_f32_16x16x32_bf16 v[36:39], v[148:151], v[224:227], v[36:39]
	v_mfma_f32_16x16x32_bf16 v[40:43], v[140:143], v[224:227], v[40:43]
	s_setprio 0
	s_setprio 1
	v_mfma_f32_16x16x32_bf16 v[32:35], v[152:155], v[182:185], v[32:35]
	v_mfma_f32_16x16x32_bf16 v[28:31], v[174:177], v[182:185], v[28:31]
	v_mfma_f32_16x16x32_bf16 v[20:23], v[174:177], v[204:207], v[20:23]
	v_mfma_f32_16x16x32_bf16 v[24:27], v[152:155], v[204:207], v[24:27]
	v_mfma_f32_16x16x32_bf16 v[16:19], v[152:155], v[212:215], v[16:19]
	v_mfma_f32_16x16x32_bf16 v[12:15], v[174:177], v[212:215], v[12:15]
	v_mfma_f32_16x16x32_bf16 v[4:7], v[174:177], v[220:223], v[4:7]
	v_mfma_f32_16x16x32_bf16 v[8:11], v[152:155], v[220:223], v[8:11]
	v_mfma_f32_16x16x32_bf16 v[32:35], v[170:173], v[192:195], v[32:35]
	v_mfma_f32_16x16x32_bf16 v[28:31], v[178:181], v[192:195], v[28:31]
	v_mfma_f32_16x16x32_bf16 v[20:23], v[178:181], v[208:211], v[20:23]
	v_mfma_f32_16x16x32_bf16 v[24:27], v[170:173], v[208:211], v[24:27]
	v_mfma_f32_16x16x32_bf16 v[16:19], v[170:173], v[216:219], v[16:19]
	v_mfma_f32_16x16x32_bf16 v[12:15], v[178:181], v[216:219], v[12:15]
	v_mfma_f32_16x16x32_bf16 v[4:7], v[178:181], v[224:227], v[4:7]
	v_mfma_f32_16x16x32_bf16 v[8:11], v[170:173], v[224:227], v[8:11]
	s_setprio 0
	s_barrier
	s_add_i32 s66, s66, 2
	s_add_u32 s10, s10, 0x100
	s_addc_u32 s11, s11, 0
	s_cmp_gt_u32 s66, 29
	s_cbranch_scc0 .LBB0_866
	s_and_b64 vcc, exec, s[12:13]
	s_cbranch_vccz .LBB0_869
	s_barrier
